# k-loop LDS fragment reads interleaved between MFMAs and MFMA order sharing the B fragment (on top of priority 2/1 k-loops)
# speedup vs baseline: 1.0026x; 1.0026x over previous
; #define G_MMA(ks_) __builtin_amdgcn_s_setprio(1); _Pragma("unroll") for (int m = 0; m < 4; ++m) \
;         _Pragma("unroll") for (int n = 0; n < 4; ++n) acc[m][n] = __builtin_amdgcn_mfma_f32_16x16x32_bf16(bfv##ks_[n], af##ks_[m], acc[m][n], 0, 0, 0); __builtin_amdgcn_s_setprio(0);
; template <class Epi>
; DEV void gemm_tile(const bf16_t* __restrict__ A, int lda, const bf16_t* __restrict__ Bt, int ldb, int K, int tm, int tn, char* smem, const Epi& epi) {
;     ...
;     for (int kt = 0; kt < nk; ++kt) {
;         const int cur = kt & 1;
;         if (kt + 1 < nk) G_DMA(cur ^ 1, kt + 1);
;         {
;             G_FRAGS(cur, 0)
;             G_MMA(0)
;             G_FRAGS(cur, 1)
;             G_MMA(1)
;         }
;         asm volatile("s_waitcnt vmcnt(0)" ::: "memory");
;         __syncthreads();
.Lgemm_up_loop:
	s_waitcnt lgkmcnt(0)
	v_mfma_f32_16x16x32_bf16 v[2:5], v[102:105], v[70:73], v[2:5]
	ds_read_b128 v[118:121], v150
	v_mfma_f32_16x16x32_bf16 v[18:21], v[102:105], v[90:93], v[18:21]
	v_mfma_f32_16x16x32_bf16 v[34:37], v[102:105], v[94:97], v[34:37]
	ds_read_b128 v[122:125], v150 offset:2048
	v_mfma_f32_16x16x32_bf16 v[50:53], v[102:105], v[98:101], v[50:53]
	v_mfma_f32_16x16x32_bf16 v[6:9], v[106:109], v[70:73], v[6:9]
	ds_read_b128 v[126:129], v150 offset:4096
	v_mfma_f32_16x16x32_bf16 v[22:25], v[106:109], v[90:93], v[22:25]
	v_mfma_f32_16x16x32_bf16 v[38:41], v[106:109], v[94:97], v[38:41]
	ds_read_b128 v[130:133], v150 offset:6144
	v_mfma_f32_16x16x32_bf16 v[54:57], v[106:109], v[98:101], v[54:57]
	v_mfma_f32_16x16x32_bf16 v[10:13], v[110:113], v[70:73], v[10:13]
	ds_read_b128 v[134:137], v152 offset:32768
	v_mfma_f32_16x16x32_bf16 v[26:29], v[110:113], v[90:93], v[26:29]
	v_mfma_f32_16x16x32_bf16 v[42:45], v[110:113], v[94:97], v[42:45]
	ds_read_b128 v[138:141], v152 offset:34816
	v_mfma_f32_16x16x32_bf16 v[58:61], v[110:113], v[98:101], v[58:61]
	v_mfma_f32_16x16x32_bf16 v[14:17], v[114:117], v[70:73], v[14:17]
	ds_read_b128 v[142:145], v152 offset:36864
	v_mfma_f32_16x16x32_bf16 v[30:33], v[114:117], v[90:93], v[30:33]
	v_mfma_f32_16x16x32_bf16 v[46:49], v[114:117], v[94:97], v[46:49]
	ds_read_b128 v[146:149], v152 offset:38912
	v_mfma_f32_16x16x32_bf16 v[62:65], v[114:117], v[98:101], v[62:65]
	s_waitcnt vmcnt(0) lgkmcnt(0)
	s_barrier
	s_mov_b32 m0, s93
	v_mfma_f32_16x16x32_bf16 v[2:5], v[134:137], v[118:121], v[2:5]
	global_load_lds_dwordx4 v250, s[88:89]
	s_add_u32 m0, m0, 0x1000
	ds_read_b128 v[70:73], v89 offset:16384
	v_mfma_f32_16x16x32_bf16 v[18:21], v[134:137], v[122:125], v[18:21]
	global_load_lds_dwordx4 v249, s[88:89]
	s_add_u32 m0, m0, 0x1000
	ds_read_b128 v[90:93], v89 offset:18432
	v_mfma_f32_16x16x32_bf16 v[34:37], v[134:137], v[126:129], v[34:37]
	global_load_lds_dwordx4 v248, s[88:89]
	s_add_u32 m0, m0, 0x1000
	ds_read_b128 v[94:97], v89 offset:20480
	v_mfma_f32_16x16x32_bf16 v[50:53], v[134:137], v[130:133], v[50:53]
	global_load_lds_dwordx4 v247, s[88:89]
	s_add_u32 m0, m0, 0x5000
	ds_read_b128 v[98:101], v89 offset:22528
	v_mfma_f32_16x16x32_bf16 v[6:9], v[138:141], v[118:121], v[6:9]
	global_load_lds_dwordx4 v246, s[90:91]
	s_add_u32 m0, m0, 0x1000
	ds_read_b128 v[102:105], v151 offset:49152
	v_mfma_f32_16x16x32_bf16 v[22:25], v[138:141], v[122:125], v[22:25]
	global_load_lds_dwordx4 v245, s[90:91]
	s_add_u32 m0, m0, 0x1000
	ds_read_b128 v[106:109], v151 offset:51200
	v_mfma_f32_16x16x32_bf16 v[38:41], v[138:141], v[126:129], v[38:41]
	global_load_lds_dwordx4 v244, s[90:91]
	s_add_u32 m0, m0, 0x1000
	ds_read_b128 v[110:113], v151 offset:53248
	v_mfma_f32_16x16x32_bf16 v[54:57], v[138:141], v[130:133], v[54:57]
	global_load_lds_dwordx4 v243, s[90:91]
	ds_read_b128 v[114:117], v151 offset:55296
	v_mfma_f32_16x16x32_bf16 v[10:13], v[142:145], v[118:121], v[10:13]
	s_add_u32 s88, s88, 0x80
	v_mfma_f32_16x16x32_bf16 v[26:29], v[142:145], v[122:125], v[26:29]
	s_addc_u32 s89, s89, 0
	v_mfma_f32_16x16x32_bf16 v[42:45], v[142:145], v[126:129], v[42:45]
	s_add_u32 s90, s90, 0x80
	v_mfma_f32_16x16x32_bf16 v[58:61], v[142:145], v[130:133], v[58:61]
	s_addc_u32 s91, s91, 0
	v_mfma_f32_16x16x32_bf16 v[14:17], v[146:149], v[118:121], v[14:17]
	v_mfma_f32_16x16x32_bf16 v[30:33], v[146:149], v[122:125], v[30:33]
	v_mfma_f32_16x16x32_bf16 v[46:49], v[146:149], v[126:129], v[46:49]
	v_mfma_f32_16x16x32_bf16 v[62:65], v[146:149], v[130:133], v[62:65]
	s_waitcnt lgkmcnt(0)
	v_mfma_f32_16x16x32_bf16 v[2:5], v[102:105], v[70:73], v[2:5]
	ds_read_b128 v[118:121], v150 offset:16384
	v_mfma_f32_16x16x32_bf16 v[18:21], v[102:105], v[90:93], v[18:21]
	v_mfma_f32_16x16x32_bf16 v[34:37], v[102:105], v[94:97], v[34:37]
	ds_read_b128 v[122:125], v150 offset:18432
	v_mfma_f32_16x16x32_bf16 v[50:53], v[102:105], v[98:101], v[50:53]
	v_mfma_f32_16x16x32_bf16 v[6:9], v[106:109], v[70:73], v[6:9]
	ds_read_b128 v[126:129], v150 offset:20480
	v_mfma_f32_16x16x32_bf16 v[22:25], v[106:109], v[90:93], v[22:25]
	v_mfma_f32_16x16x32_bf16 v[38:41], v[106:109], v[94:97], v[38:41]
	ds_read_b128 v[130:133], v150 offset:22528
	v_mfma_f32_16x16x32_bf16 v[54:57], v[106:109], v[98:101], v[54:57]
	v_mfma_f32_16x16x32_bf16 v[10:13], v[110:113], v[70:73], v[10:13]
	ds_read_b128 v[134:137], v152 offset:49152
	v_mfma_f32_16x16x32_bf16 v[26:29], v[110:113], v[90:93], v[26:29]
	v_mfma_f32_16x16x32_bf16 v[42:45], v[110:113], v[94:97], v[42:45]
	ds_read_b128 v[138:141], v152 offset:51200
	v_mfma_f32_16x16x32_bf16 v[58:61], v[110:113], v[98:101], v[58:61]
	v_mfma_f32_16x16x32_bf16 v[14:17], v[114:117], v[70:73], v[14:17]
	ds_read_b128 v[142:145], v152 offset:53248
	v_mfma_f32_16x16x32_bf16 v[30:33], v[114:117], v[90:93], v[30:33]
	v_mfma_f32_16x16x32_bf16 v[46:49], v[114:117], v[94:97], v[46:49]
	ds_read_b128 v[146:149], v152 offset:55296
	v_mfma_f32_16x16x32_bf16 v[62:65], v[114:117], v[98:101], v[62:65]
	s_waitcnt vmcnt(0) lgkmcnt(0)
	s_barrier
; #define G_MMA(ks_) __builtin_amdgcn_s_setprio(1); _Pragma("unroll") for (int m = 0; m < 4; ++m) \
;         _Pragma("unroll") for (int n = 0; n < 4; ++n) acc[m][n] = __builtin_amdgcn_mfma_f32_16x16x32_bf16(bfv##ks_[n], af##ks_[m], acc[m][n], 0, 0, 0); __builtin_amdgcn_s_setprio(0);
; template <class Epi>
; DEV void gemm_tile(const bf16_t* __restrict__ A, int lda, const bf16_t* __restrict__ Bt, int ldb, int K, int tm, int tn, char* smem, const Epi& epi) {
;     ...
;     for (int kt = 0; kt < nk; ++kt) {
;         const int cur = kt & 1;
;         if (kt + 1 < nk) G_DMA(cur ^ 1, kt + 1);
;         {
;             G_FRAGS(cur, 0)
;             G_MMA(0)
;             G_FRAGS(cur, 1)
;             G_MMA(1)
;         }
;         asm volatile("s_waitcnt vmcnt(0)" ::: "memory");
;         __syncthreads();
;     }
	s_mov_b32 m0, s94
	v_mfma_f32_16x16x32_bf16 v[2:5], v[134:137], v[118:121], v[2:5]
	global_load_lds_dwordx4 v250, s[88:89]
	s_add_u32 m0, m0, 0x1000
	ds_read_b128 v[70:73], v89
	v_mfma_f32_16x16x32_bf16 v[18:21], v[134:137], v[122:125], v[18:21]
	global_load_lds_dwordx4 v249, s[88:89]
	s_add_u32 m0, m0, 0x1000
	ds_read_b128 v[90:93], v89 offset:2048
	v_mfma_f32_16x16x32_bf16 v[34:37], v[134:137], v[126:129], v[34:37]
	global_load_lds_dwordx4 v248, s[88:89]
	s_add_u32 m0, m0, 0x1000
	ds_read_b128 v[94:97], v89 offset:4096
	v_mfma_f32_16x16x32_bf16 v[50:53], v[134:137], v[130:133], v[50:53]
	global_load_lds_dwordx4 v247, s[88:89]
	s_add_u32 m0, m0, 0x5000
	ds_read_b128 v[98:101], v89 offset:6144
	v_mfma_f32_16x16x32_bf16 v[6:9], v[138:141], v[118:121], v[6:9]
	global_load_lds_dwordx4 v246, s[90:91]
	s_add_u32 m0, m0, 0x1000
	ds_read_b128 v[102:105], v151 offset:32768
	v_mfma_f32_16x16x32_bf16 v[22:25], v[138:141], v[122:125], v[22:25]
	global_load_lds_dwordx4 v245, s[90:91]
	s_add_u32 m0, m0, 0x1000
	ds_read_b128 v[106:109], v151 offset:34816
	v_mfma_f32_16x16x32_bf16 v[38:41], v[138:141], v[126:129], v[38:41]
	global_load_lds_dwordx4 v244, s[90:91]
	s_add_u32 m0, m0, 0x1000
	ds_read_b128 v[110:113], v151 offset:36864
	v_mfma_f32_16x16x32_bf16 v[54:57], v[138:141], v[130:133], v[54:57]
	global_load_lds_dwordx4 v243, s[90:91]
	ds_read_b128 v[114:117], v151 offset:38912
	v_mfma_f32_16x16x32_bf16 v[10:13], v[142:145], v[118:121], v[10:13]
	s_add_u32 s88, s88, 0x80
	v_mfma_f32_16x16x32_bf16 v[26:29], v[142:145], v[122:125], v[26:29]
	s_addc_u32 s89, s89, 0
	v_mfma_f32_16x16x32_bf16 v[42:45], v[142:145], v[126:129], v[42:45]
	s_add_u32 s90, s90, 0x80
	v_mfma_f32_16x16x32_bf16 v[58:61], v[142:145], v[130:133], v[58:61]
	s_addc_u32 s91, s91, 0
	v_mfma_f32_16x16x32_bf16 v[14:17], v[146:149], v[118:121], v[14:17]
	v_mfma_f32_16x16x32_bf16 v[30:33], v[146:149], v[122:125], v[30:33]
	v_mfma_f32_16x16x32_bf16 v[46:49], v[146:149], v[126:129], v[46:49]
	v_mfma_f32_16x16x32_bf16 v[62:65], v[146:149], v[130:133], v[62:65]
	s_sub_u32 s92, s92, 1
	s_cmp_lg_u32 s92, 0
	s_cbranch_scc1 .Lgemm_up_loop
	s_waitcnt lgkmcnt(0)
	v_mfma_f32_16x16x32_bf16 v[2:5], v[102:105], v[70:73], v[2:5]
	ds_read_b128 v[118:121], v150
	v_mfma_f32_16x16x32_bf16 v[18:21], v[102:105], v[90:93], v[18:21]
	v_mfma_f32_16x16x32_bf16 v[34:37], v[102:105], v[94:97], v[34:37]
	ds_read_b128 v[122:125], v150 offset:2048
	v_mfma_f32_16x16x32_bf16 v[50:53], v[102:105], v[98:101], v[50:53]
	v_mfma_f32_16x16x32_bf16 v[6:9], v[106:109], v[70:73], v[6:9]
	ds_read_b128 v[126:129], v150 offset:4096
	v_mfma_f32_16x16x32_bf16 v[22:25], v[106:109], v[90:93], v[22:25]
	v_mfma_f32_16x16x32_bf16 v[38:41], v[106:109], v[94:97], v[38:41]
	ds_read_b128 v[130:133], v150 offset:6144
	v_mfma_f32_16x16x32_bf16 v[54:57], v[106:109], v[98:101], v[54:57]
	v_mfma_f32_16x16x32_bf16 v[10:13], v[110:113], v[70:73], v[10:13]
	ds_read_b128 v[134:137], v152 offset:32768
	v_mfma_f32_16x16x32_bf16 v[26:29], v[110:113], v[90:93], v[26:29]
	v_mfma_f32_16x16x32_bf16 v[42:45], v[110:113], v[94:97], v[42:45]
	ds_read_b128 v[138:141], v152 offset:34816
	v_mfma_f32_16x16x32_bf16 v[58:61], v[110:113], v[98:101], v[58:61]
	v_mfma_f32_16x16x32_bf16 v[14:17], v[114:117], v[70:73], v[14:17]
	ds_read_b128 v[142:145], v152 offset:36864
	v_mfma_f32_16x16x32_bf16 v[30:33], v[114:117], v[90:93], v[30:33]
	v_mfma_f32_16x16x32_bf16 v[46:49], v[114:117], v[94:97], v[46:49]
	ds_read_b128 v[146:149], v152 offset:38912
	v_mfma_f32_16x16x32_bf16 v[62:65], v[114:117], v[98:101], v[62:65]
	s_waitcnt vmcnt(0) lgkmcnt(0)
	s_barrier
; #define G_MMA(ks_) __builtin_amdgcn_s_setprio(1); _Pragma("unroll") for (int m = 0; m < 4; ++m) \
;         _Pragma("unroll") for (int n = 0; n < 4; ++n) acc[m][n] = __builtin_amdgcn_mfma_f32_16x16x32_bf16(bfv##ks_[n], af##ks_[m], acc[m][n], 0, 0, 0); __builtin_amdgcn_s_setprio(0);
; template <class Epi>
; DEV void gemm_tile(const bf16_t* __restrict__ A, int lda, const bf16_t* __restrict__ Bt, int ldb, int K, int tm, int tn, char* smem, const Epi& epi) {
;     ...
;     for (int kt = 0; kt < nk; ++kt) {
;         const int cur = kt & 1;
;         if (kt + 1 < nk) G_DMA(cur ^ 1, kt + 1);
;         {
;             G_FRAGS(cur, 0)
;             G_MMA(0)
;             G_FRAGS(cur, 1)
;             G_MMA(1)
;         }
;         asm volatile("s_waitcnt vmcnt(0)" ::: "memory");
;         __syncthreads();
;     }
	v_mfma_f32_16x16x32_bf16 v[2:5], v[134:137], v[118:121], v[2:5]
	ds_read_b128 v[70:73], v89 offset:16384
	v_mfma_f32_16x16x32_bf16 v[18:21], v[134:137], v[122:125], v[18:21]
	ds_read_b128 v[90:93], v89 offset:18432
	v_mfma_f32_16x16x32_bf16 v[34:37], v[134:137], v[126:129], v[34:37]
	ds_read_b128 v[94:97], v89 offset:20480
	v_mfma_f32_16x16x32_bf16 v[50:53], v[134:137], v[130:133], v[50:53]
	ds_read_b128 v[98:101], v89 offset:22528
	v_mfma_f32_16x16x32_bf16 v[6:9], v[138:141], v[118:121], v[6:9]
	ds_read_b128 v[102:105], v151 offset:49152
	v_mfma_f32_16x16x32_bf16 v[22:25], v[138:141], v[122:125], v[22:25]
	ds_read_b128 v[106:109], v151 offset:51200
	v_mfma_f32_16x16x32_bf16 v[38:41], v[138:141], v[126:129], v[38:41]
	ds_read_b128 v[110:113], v151 offset:53248
	v_mfma_f32_16x16x32_bf16 v[54:57], v[138:141], v[130:133], v[54:57]
	ds_read_b128 v[114:117], v151 offset:55296
	v_mfma_f32_16x16x32_bf16 v[10:13], v[142:145], v[118:121], v[10:13]
	v_mfma_f32_16x16x32_bf16 v[26:29], v[142:145], v[122:125], v[26:29]
	v_mfma_f32_16x16x32_bf16 v[42:45], v[142:145], v[126:129], v[42:45]
	v_mfma_f32_16x16x32_bf16 v[58:61], v[142:145], v[130:133], v[58:61]
	v_mfma_f32_16x16x32_bf16 v[14:17], v[146:149], v[118:121], v[14:17]
	v_mfma_f32_16x16x32_bf16 v[30:33], v[146:149], v[122:125], v[30:33]
	v_mfma_f32_16x16x32_bf16 v[46:49], v[146:149], v[126:129], v[46:49]
	v_mfma_f32_16x16x32_bf16 v[62:65], v[146:149], v[130:133], v[62:65]
	s_waitcnt lgkmcnt(0)
	v_mfma_f32_16x16x32_bf16 v[2:5], v[102:105], v[70:73], v[2:5]
	ds_read_b128 v[118:121], v150 offset:16384
	v_mfma_f32_16x16x32_bf16 v[18:21], v[102:105], v[90:93], v[18:21]
	v_mfma_f32_16x16x32_bf16 v[34:37], v[102:105], v[94:97], v[34:37]
	ds_read_b128 v[122:125], v150 offset:18432
	v_mfma_f32_16x16x32_bf16 v[50:53], v[102:105], v[98:101], v[50:53]
	v_mfma_f32_16x16x32_bf16 v[6:9], v[106:109], v[70:73], v[6:9]
	ds_read_b128 v[126:129], v150 offset:20480
	v_mfma_f32_16x16x32_bf16 v[22:25], v[106:109], v[90:93], v[22:25]
	v_mfma_f32_16x16x32_bf16 v[38:41], v[106:109], v[94:97], v[38:41]
	ds_read_b128 v[130:133], v150 offset:22528
	v_mfma_f32_16x16x32_bf16 v[54:57], v[106:109], v[98:101], v[54:57]
	v_mfma_f32_16x16x32_bf16 v[10:13], v[110:113], v[70:73], v[10:13]
	ds_read_b128 v[134:137], v152 offset:49152
	v_mfma_f32_16x16x32_bf16 v[26:29], v[110:113], v[90:93], v[26:29]
	v_mfma_f32_16x16x32_bf16 v[42:45], v[110:113], v[94:97], v[42:45]
	ds_read_b128 v[138:141], v152 offset:51200
	v_mfma_f32_16x16x32_bf16 v[58:61], v[110:113], v[98:101], v[58:61]
	v_mfma_f32_16x16x32_bf16 v[14:17], v[114:117], v[70:73], v[14:17]
	ds_read_b128 v[142:145], v152 offset:53248
	v_mfma_f32_16x16x32_bf16 v[30:33], v[114:117], v[90:93], v[30:33]
	v_mfma_f32_16x16x32_bf16 v[46:49], v[114:117], v[94:97], v[46:49]
	ds_read_b128 v[146:149], v152 offset:55296
	v_mfma_f32_16x16x32_bf16 v[62:65], v[114:117], v[98:101], v[62:65]
	s_waitcnt lgkmcnt(0)
	s_barrier
	v_mfma_f32_16x16x32_bf16 v[2:5], v[134:137], v[118:121], v[2:5]
	v_mfma_f32_16x16x32_bf16 v[18:21], v[134:137], v[122:125], v[18:21]
	v_mfma_f32_16x16x32_bf16 v[34:37], v[134:137], v[126:129], v[34:37]
	v_mfma_f32_16x16x32_bf16 v[50:53], v[134:137], v[130:133], v[50:53]
	v_mfma_f32_16x16x32_bf16 v[6:9], v[138:141], v[118:121], v[6:9]
	v_mfma_f32_16x16x32_bf16 v[22:25], v[138:141], v[122:125], v[22:25]
	v_mfma_f32_16x16x32_bf16 v[38:41], v[138:141], v[126:129], v[38:41]
	v_mfma_f32_16x16x32_bf16 v[54:57], v[138:141], v[130:133], v[54:57]
	v_mfma_f32_16x16x32_bf16 v[10:13], v[142:145], v[118:121], v[10:13]
	v_mfma_f32_16x16x32_bf16 v[26:29], v[142:145], v[122:125], v[26:29]
	v_mfma_f32_16x16x32_bf16 v[42:45], v[142:145], v[126:129], v[42:45]
	v_mfma_f32_16x16x32_bf16 v[58:61], v[142:145], v[130:133], v[58:61]
	v_mfma_f32_16x16x32_bf16 v[14:17], v[146:149], v[118:121], v[14:17]
	v_mfma_f32_16x16x32_bf16 v[30:33], v[146:149], v[122:125], v[30:33]
	v_mfma_f32_16x16x32_bf16 v[46:49], v[146:149], v[126:129], v[46:49]
	v_mfma_f32_16x16x32_bf16 v[62:65], v[146:149], v[130:133], v[62:65]
	s_setprio 0
	v_readlane_b32 s88, v255, 24
	v_readlane_b32 s89, v255, 25
	v_readlane_b32 s90, v255, 26
	v_readlane_b32 s91, v255, 27
	v_readlane_b32 s92, v255, 28
	v_readlane_b32 s93, v255, 29
	v_readlane_b32 s94, v255, 30
	v_readlane_b32 s95, v255, 31
	s_nop 7
	s_nop 1

; #define G_MMA(ks_) __builtin_amdgcn_s_setprio(1); _Pragma("unroll") for (int m = 0; m < 4; ++m) \
;         _Pragma("unroll") for (int n = 0; n < 4; ++n) acc[m][n] = __builtin_amdgcn_mfma_f32_16x16x32_bf16(bfv##ks_[n], af##ks_[m], acc[m][n], 0, 0, 0); __builtin_amdgcn_s_setprio(0);
; template <class Epi>
; DEV void gemm_tile(const bf16_t* __restrict__ A, int lda, const bf16_t* __restrict__ Bt, int ldb, int K, int tm, int tn, char* smem, const Epi& epi) {
;     ...
;     for (int kt = 0; kt < nk; ++kt) {
;         const int cur = kt & 1;
;         if (kt + 1 < nk) G_DMA(cur ^ 1, kt + 1);
;         {
;             G_FRAGS(cur, 0)
;             G_MMA(0)
;             G_FRAGS(cur, 1)
;             G_MMA(1)
;         }
;         asm volatile("s_waitcnt vmcnt(0)" ::: "memory");
;         __syncthreads();
.Lgemm_out_loop:
	s_waitcnt lgkmcnt(0)
	v_mfma_f32_16x16x32_bf16 v[62:65], v[142:145], v[126:129], v[62:65]
	ds_read_b128 v[158:161], v214
	v_mfma_f32_16x16x32_bf16 v[18:21], v[142:145], v[130:133], v[18:21]
	v_mfma_f32_16x16x32_bf16 v[22:25], v[142:145], v[134:137], v[22:25]
	ds_read_b128 v[164:167], v214 offset:2048
	v_mfma_f32_16x16x32_bf16 v[44:47], v[142:145], v[138:141], v[44:47]
	v_mfma_f32_16x16x32_bf16 v[66:69], v[146:149], v[126:129], v[66:69]
	ds_read_b128 v[168:171], v214 offset:4096
	v_mfma_f32_16x16x32_bf16 v[28:31], v[146:149], v[130:133], v[28:31]
	v_mfma_f32_16x16x32_bf16 v[32:35], v[146:149], v[134:137], v[32:35]
	ds_read_b128 v[172:175], v214 offset:6144
	v_mfma_f32_16x16x32_bf16 v[48:51], v[146:149], v[138:141], v[48:51]
	v_mfma_f32_16x16x32_bf16 v[70:73], v[150:153], v[126:129], v[70:73]
	ds_read_b128 v[176:179], v216 offset:32768
	v_mfma_f32_16x16x32_bf16 v[56:59], v[150:153], v[130:133], v[56:59]
	v_mfma_f32_16x16x32_bf16 v[74:77], v[150:153], v[134:137], v[74:77]
	ds_read_b128 v[180:183], v216 offset:34816
	v_mfma_f32_16x16x32_bf16 v[52:55], v[150:153], v[138:141], v[52:55]
	v_mfma_f32_16x16x32_bf16 v[2:5], v[154:157], v[126:129], v[2:5]
	ds_read_b128 v[192:195], v216 offset:36864
	v_mfma_f32_16x16x32_bf16 v[10:13], v[154:157], v[130:133], v[10:13]
	v_mfma_f32_16x16x32_bf16 v[36:39], v[154:157], v[134:137], v[36:39]
	ds_read_b128 v[210:213], v216 offset:38912
	v_mfma_f32_16x16x32_bf16 v[14:17], v[154:157], v[138:141], v[14:17]
	s_waitcnt vmcnt(0) lgkmcnt(0)
	s_barrier
	s_mov_b32 m0, s93
	v_mfma_f32_16x16x32_bf16 v[62:65], v[176:179], v[158:161], v[62:65]
	global_load_lds_dwordx4 v250, s[88:89]
	s_add_u32 m0, m0, 0x1000
	ds_read_b128 v[126:129], v184 offset:16384
	v_mfma_f32_16x16x32_bf16 v[18:21], v[176:179], v[164:167], v[18:21]
	global_load_lds_dwordx4 v249, s[88:89]
	s_add_u32 m0, m0, 0x1000
	ds_read_b128 v[130:133], v184 offset:18432
	v_mfma_f32_16x16x32_bf16 v[22:25], v[176:179], v[168:171], v[22:25]
	global_load_lds_dwordx4 v248, s[88:89]
	s_add_u32 m0, m0, 0x1000
	ds_read_b128 v[134:137], v184 offset:20480
	v_mfma_f32_16x16x32_bf16 v[44:47], v[176:179], v[172:175], v[44:47]
	global_load_lds_dwordx4 v247, s[88:89]
	s_add_u32 m0, m0, 0x5000
	ds_read_b128 v[138:141], v184 offset:22528
	v_mfma_f32_16x16x32_bf16 v[66:69], v[180:183], v[158:161], v[66:69]
	global_load_lds_dwordx4 v246, s[90:91]
	s_add_u32 m0, m0, 0x1000
	ds_read_b128 v[142:145], v215 offset:49152
	v_mfma_f32_16x16x32_bf16 v[28:31], v[180:183], v[164:167], v[28:31]
	global_load_lds_dwordx4 v245, s[90:91]
	s_add_u32 m0, m0, 0x1000
	ds_read_b128 v[146:149], v215 offset:51200
	v_mfma_f32_16x16x32_bf16 v[32:35], v[180:183], v[168:171], v[32:35]
	global_load_lds_dwordx4 v244, s[90:91]
	s_add_u32 m0, m0, 0x1000
	ds_read_b128 v[150:153], v215 offset:53248
	v_mfma_f32_16x16x32_bf16 v[48:51], v[180:183], v[172:175], v[48:51]
	global_load_lds_dwordx4 v243, s[90:91]
	ds_read_b128 v[154:157], v215 offset:55296
	v_mfma_f32_16x16x32_bf16 v[70:73], v[192:195], v[158:161], v[70:73]
	s_add_u32 s88, s88, 0x80
	v_mfma_f32_16x16x32_bf16 v[56:59], v[192:195], v[164:167], v[56:59]
	s_addc_u32 s89, s89, 0
	v_mfma_f32_16x16x32_bf16 v[74:77], v[192:195], v[168:171], v[74:77]
	s_add_u32 s90, s90, 0x80
	v_mfma_f32_16x16x32_bf16 v[52:55], v[192:195], v[172:175], v[52:55]
	s_addc_u32 s91, s91, 0
	v_mfma_f32_16x16x32_bf16 v[2:5], v[210:213], v[158:161], v[2:5]
	v_mfma_f32_16x16x32_bf16 v[10:13], v[210:213], v[164:167], v[10:13]
	v_mfma_f32_16x16x32_bf16 v[36:39], v[210:213], v[168:171], v[36:39]
	v_mfma_f32_16x16x32_bf16 v[14:17], v[210:213], v[172:175], v[14:17]
	s_waitcnt lgkmcnt(0)
	v_mfma_f32_16x16x32_bf16 v[62:65], v[142:145], v[126:129], v[62:65]
	ds_read_b128 v[158:161], v214 offset:16384
	v_mfma_f32_16x16x32_bf16 v[18:21], v[142:145], v[130:133], v[18:21]
	v_mfma_f32_16x16x32_bf16 v[22:25], v[142:145], v[134:137], v[22:25]
	ds_read_b128 v[164:167], v214 offset:18432
	v_mfma_f32_16x16x32_bf16 v[44:47], v[142:145], v[138:141], v[44:47]
	v_mfma_f32_16x16x32_bf16 v[66:69], v[146:149], v[126:129], v[66:69]
	ds_read_b128 v[168:171], v214 offset:20480
	v_mfma_f32_16x16x32_bf16 v[28:31], v[146:149], v[130:133], v[28:31]
	v_mfma_f32_16x16x32_bf16 v[32:35], v[146:149], v[134:137], v[32:35]
	ds_read_b128 v[172:175], v214 offset:22528
	v_mfma_f32_16x16x32_bf16 v[48:51], v[146:149], v[138:141], v[48:51]
	v_mfma_f32_16x16x32_bf16 v[70:73], v[150:153], v[126:129], v[70:73]
	ds_read_b128 v[176:179], v216 offset:49152
	v_mfma_f32_16x16x32_bf16 v[56:59], v[150:153], v[130:133], v[56:59]
	v_mfma_f32_16x16x32_bf16 v[74:77], v[150:153], v[134:137], v[74:77]
	ds_read_b128 v[180:183], v216 offset:51200
	v_mfma_f32_16x16x32_bf16 v[52:55], v[150:153], v[138:141], v[52:55]
	v_mfma_f32_16x16x32_bf16 v[2:5], v[154:157], v[126:129], v[2:5]
	ds_read_b128 v[192:195], v216 offset:53248
	v_mfma_f32_16x16x32_bf16 v[10:13], v[154:157], v[130:133], v[10:13]
	v_mfma_f32_16x16x32_bf16 v[36:39], v[154:157], v[134:137], v[36:39]
	ds_read_b128 v[210:213], v216 offset:55296
	v_mfma_f32_16x16x32_bf16 v[14:17], v[154:157], v[138:141], v[14:17]
	s_waitcnt vmcnt(0) lgkmcnt(0)
	s_barrier
; #define G_MMA(ks_) __builtin_amdgcn_s_setprio(1); _Pragma("unroll") for (int m = 0; m < 4; ++m) \
;         _Pragma("unroll") for (int n = 0; n < 4; ++n) acc[m][n] = __builtin_amdgcn_mfma_f32_16x16x32_bf16(bfv##ks_[n], af##ks_[m], acc[m][n], 0, 0, 0); __builtin_amdgcn_s_setprio(0);
; template <class Epi>
; DEV void gemm_tile(const bf16_t* __restrict__ A, int lda, const bf16_t* __restrict__ Bt, int ldb, int K, int tm, int tn, char* smem, const Epi& epi) {
;     ...
;     for (int kt = 0; kt < nk; ++kt) {
;         const int cur = kt & 1;
;         if (kt + 1 < nk) G_DMA(cur ^ 1, kt + 1);
;         {
;             G_FRAGS(cur, 0)
;             G_MMA(0)
;             G_FRAGS(cur, 1)
;             G_MMA(1)
;         }
;         asm volatile("s_waitcnt vmcnt(0)" ::: "memory");
;         __syncthreads();
;     }
	s_mov_b32 m0, s94
	v_mfma_f32_16x16x32_bf16 v[62:65], v[176:179], v[158:161], v[62:65]
	global_load_lds_dwordx4 v250, s[88:89]
	s_add_u32 m0, m0, 0x1000
	ds_read_b128 v[126:129], v184
	v_mfma_f32_16x16x32_bf16 v[18:21], v[176:179], v[164:167], v[18:21]
	global_load_lds_dwordx4 v249, s[88:89]
	s_add_u32 m0, m0, 0x1000
	ds_read_b128 v[130:133], v184 offset:2048
	v_mfma_f32_16x16x32_bf16 v[22:25], v[176:179], v[168:171], v[22:25]
	global_load_lds_dwordx4 v248, s[88:89]
	s_add_u32 m0, m0, 0x1000
	ds_read_b128 v[134:137], v184 offset:4096
	v_mfma_f32_16x16x32_bf16 v[44:47], v[176:179], v[172:175], v[44:47]
	global_load_lds_dwordx4 v247, s[88:89]
	s_add_u32 m0, m0, 0x5000
	ds_read_b128 v[138:141], v184 offset:6144
	v_mfma_f32_16x16x32_bf16 v[66:69], v[180:183], v[158:161], v[66:69]
	global_load_lds_dwordx4 v246, s[90:91]
	s_add_u32 m0, m0, 0x1000
	ds_read_b128 v[142:145], v215 offset:32768
	v_mfma_f32_16x16x32_bf16 v[28:31], v[180:183], v[164:167], v[28:31]
	global_load_lds_dwordx4 v245, s[90:91]
	s_add_u32 m0, m0, 0x1000
	ds_read_b128 v[146:149], v215 offset:34816
	v_mfma_f32_16x16x32_bf16 v[32:35], v[180:183], v[168:171], v[32:35]
	global_load_lds_dwordx4 v244, s[90:91]
	s_add_u32 m0, m0, 0x1000
	ds_read_b128 v[150:153], v215 offset:36864
	v_mfma_f32_16x16x32_bf16 v[48:51], v[180:183], v[172:175], v[48:51]
	global_load_lds_dwordx4 v243, s[90:91]
	ds_read_b128 v[154:157], v215 offset:38912
	v_mfma_f32_16x16x32_bf16 v[70:73], v[192:195], v[158:161], v[70:73]
	s_add_u32 s88, s88, 0x80
	v_mfma_f32_16x16x32_bf16 v[56:59], v[192:195], v[164:167], v[56:59]
	s_addc_u32 s89, s89, 0
	v_mfma_f32_16x16x32_bf16 v[74:77], v[192:195], v[168:171], v[74:77]
	s_add_u32 s90, s90, 0x80
	v_mfma_f32_16x16x32_bf16 v[52:55], v[192:195], v[172:175], v[52:55]
	s_addc_u32 s91, s91, 0
	v_mfma_f32_16x16x32_bf16 v[2:5], v[210:213], v[158:161], v[2:5]
	v_mfma_f32_16x16x32_bf16 v[10:13], v[210:213], v[164:167], v[10:13]
	v_mfma_f32_16x16x32_bf16 v[36:39], v[210:213], v[168:171], v[36:39]
	v_mfma_f32_16x16x32_bf16 v[14:17], v[210:213], v[172:175], v[14:17]
	s_sub_u32 s92, s92, 1
	s_cmp_lg_u32 s92, 0
	s_cbranch_scc1 .Lgemm_out_loop
	s_waitcnt lgkmcnt(0)
	v_mfma_f32_16x16x32_bf16 v[62:65], v[142:145], v[126:129], v[62:65]
	ds_read_b128 v[158:161], v214
	v_mfma_f32_16x16x32_bf16 v[18:21], v[142:145], v[130:133], v[18:21]
	v_mfma_f32_16x16x32_bf16 v[22:25], v[142:145], v[134:137], v[22:25]
	ds_read_b128 v[164:167], v214 offset:2048
	v_mfma_f32_16x16x32_bf16 v[44:47], v[142:145], v[138:141], v[44:47]
	v_mfma_f32_16x16x32_bf16 v[66:69], v[146:149], v[126:129], v[66:69]
	ds_read_b128 v[168:171], v214 offset:4096
	v_mfma_f32_16x16x32_bf16 v[28:31], v[146:149], v[130:133], v[28:31]
	v_mfma_f32_16x16x32_bf16 v[32:35], v[146:149], v[134:137], v[32:35]
	ds_read_b128 v[172:175], v214 offset:6144
	v_mfma_f32_16x16x32_bf16 v[48:51], v[146:149], v[138:141], v[48:51]
	v_mfma_f32_16x16x32_bf16 v[70:73], v[150:153], v[126:129], v[70:73]
	ds_read_b128 v[176:179], v216 offset:32768
	v_mfma_f32_16x16x32_bf16 v[56:59], v[150:153], v[130:133], v[56:59]
	v_mfma_f32_16x16x32_bf16 v[74:77], v[150:153], v[134:137], v[74:77]
	ds_read_b128 v[180:183], v216 offset:34816
	v_mfma_f32_16x16x32_bf16 v[52:55], v[150:153], v[138:141], v[52:55]
	v_mfma_f32_16x16x32_bf16 v[2:5], v[154:157], v[126:129], v[2:5]
	ds_read_b128 v[192:195], v216 offset:36864
	v_mfma_f32_16x16x32_bf16 v[10:13], v[154:157], v[130:133], v[10:13]
	v_mfma_f32_16x16x32_bf16 v[36:39], v[154:157], v[134:137], v[36:39]
	ds_read_b128 v[210:213], v216 offset:38912
	v_mfma_f32_16x16x32_bf16 v[14:17], v[154:157], v[138:141], v[14:17]
	s_waitcnt vmcnt(0) lgkmcnt(0)
	s_barrier
	v_mfma_f32_16x16x32_bf16 v[62:65], v[176:179], v[158:161], v[62:65]
	ds_read_b128 v[126:129], v184 offset:16384
	v_mfma_f32_16x16x32_bf16 v[18:21], v[176:179], v[164:167], v[18:21]
	ds_read_b128 v[130:133], v184 offset:18432
	v_mfma_f32_16x16x32_bf16 v[22:25], v[176:179], v[168:171], v[22:25]
	ds_read_b128 v[134:137], v184 offset:20480
	v_mfma_f32_16x16x32_bf16 v[44:47], v[176:179], v[172:175], v[44:47]
	ds_read_b128 v[138:141], v184 offset:22528
	v_mfma_f32_16x16x32_bf16 v[66:69], v[180:183], v[158:161], v[66:69]
	ds_read_b128 v[142:145], v215 offset:49152
	v_mfma_f32_16x16x32_bf16 v[28:31], v[180:183], v[164:167], v[28:31]
	ds_read_b128 v[146:149], v215 offset:51200
	v_mfma_f32_16x16x32_bf16 v[32:35], v[180:183], v[168:171], v[32:35]
	ds_read_b128 v[150:153], v215 offset:53248
	v_mfma_f32_16x16x32_bf16 v[48:51], v[180:183], v[172:175], v[48:51]
	ds_read_b128 v[154:157], v215 offset:55296
	v_mfma_f32_16x16x32_bf16 v[70:73], v[192:195], v[158:161], v[70:73]
	v_mfma_f32_16x16x32_bf16 v[56:59], v[192:195], v[164:167], v[56:59]
	v_mfma_f32_16x16x32_bf16 v[74:77], v[192:195], v[168:171], v[74:77]
	v_mfma_f32_16x16x32_bf16 v[52:55], v[192:195], v[172:175], v[52:55]
	v_mfma_f32_16x16x32_bf16 v[2:5], v[210:213], v[158:161], v[2:5]
	v_mfma_f32_16x16x32_bf16 v[10:13], v[210:213], v[164:167], v[10:13]
	v_mfma_f32_16x16x32_bf16 v[36:39], v[210:213], v[168:171], v[36:39]
	v_mfma_f32_16x16x32_bf16 v[14:17], v[210:213], v[172:175], v[14:17]
	s_waitcnt lgkmcnt(0)
	v_mfma_f32_16x16x32_bf16 v[62:65], v[142:145], v[126:129], v[62:65]
	ds_read_b128 v[158:161], v214 offset:16384
	v_mfma_f32_16x16x32_bf16 v[18:21], v[142:145], v[130:133], v[18:21]
	v_mfma_f32_16x16x32_bf16 v[22:25], v[142:145], v[134:137], v[22:25]
	ds_read_b128 v[164:167], v214 offset:18432
	v_mfma_f32_16x16x32_bf16 v[44:47], v[142:145], v[138:141], v[44:47]
	v_mfma_f32_16x16x32_bf16 v[66:69], v[146:149], v[126:129], v[66:69]
	ds_read_b128 v[168:171], v214 offset:20480
	v_mfma_f32_16x16x32_bf16 v[28:31], v[146:149], v[130:133], v[28:31]
	v_mfma_f32_16x16x32_bf16 v[32:35], v[146:149], v[134:137], v[32:35]
	ds_read_b128 v[172:175], v214 offset:22528
	v_mfma_f32_16x16x32_bf16 v[48:51], v[146:149], v[138:141], v[48:51]
	v_mfma_f32_16x16x32_bf16 v[70:73], v[150:153], v[126:129], v[70:73]
	ds_read_b128 v[176:179], v216 offset:49152
	v_mfma_f32_16x16x32_bf16 v[56:59], v[150:153], v[130:133], v[56:59]
	v_mfma_f32_16x16x32_bf16 v[74:77], v[150:153], v[134:137], v[74:77]
	ds_read_b128 v[180:183], v216 offset:51200
	v_mfma_f32_16x16x32_bf16 v[52:55], v[150:153], v[138:141], v[52:55]
	v_mfma_f32_16x16x32_bf16 v[2:5], v[154:157], v[126:129], v[2:5]
	ds_read_b128 v[192:195], v216 offset:53248
	v_mfma_f32_16x16x32_bf16 v[10:13], v[154:157], v[130:133], v[10:13]
	v_mfma_f32_16x16x32_bf16 v[36:39], v[154:157], v[134:137], v[36:39]
	ds_read_b128 v[210:213], v216 offset:55296
	v_mfma_f32_16x16x32_bf16 v[14:17], v[154:157], v[138:141], v[14:17]
	s_waitcnt lgkmcnt(0)
	s_barrier
; DEV int tid_() { int t = __builtin_amdgcn_workitem_id_x(); asm volatile("" : "+v"(t)); return t; }
; template <class Epi>
; DEV void gemm_tile(const bf16_t* __restrict__ A, int lda, const bf16_t* __restrict__ Bt, int ldb, int K, int tm, int tn, char* smem, const Epi& epi) {
;     ...
;     float* Ct = (float*)smem;
; #pragma unroll
;     for (int m = 0; m < 4; ++m)
; #pragma unroll
;         for (int n = 0; n < 4; ++n) *(f32x4*)(Ct + (wr * 64 + m * 16 + fr) * CP + wc * 64 + n * 16 + fq * 4) = acc[m][n];
;     __syncthreads();
;     DEV void operator()(int tm, int tn, const float* Ct) const {
;         const int row0 = tm * 128, b = row0 / TT, tt0 = row0 - b * TT;
;         const int tid = tid_(), c = (tid & 31) << 2, rb = tid >> 5;
;         const f32x4 g = *(const f32x4*)(mod + (size_t)(tt0 < SEQ ? b : 32) * 6144 + goff + tn * 128 + c);
;         float* x0 = xrow(*p, row0) + tn * 128 + c;
;         const float* xs = from_in ? xrow_in(*p, row0) + tn * 128 + c : x0;
; #pragma unroll
;         for (int it0 = 0; it0 < 16; it0 += 8) {
;             f32x4 xv[8];
; #pragma unroll
;             for (int u = 0; u < 8; ++u) xv[u] = *(const f32x4*)(xs + (size_t)(rb + 8 * (it0 + u)) * D);
	v_mfma_f32_16x16x32_bf16 v[62:65], v[176:179], v[158:161], v[62:65]
	v_mfma_f32_16x16x32_bf16 v[18:21], v[176:179], v[164:167], v[18:21]
	v_mfma_f32_16x16x32_bf16 v[22:25], v[176:179], v[168:171], v[22:25]
	v_mfma_f32_16x16x32_bf16 v[44:47], v[176:179], v[172:175], v[44:47]
	v_mfma_f32_16x16x32_bf16 v[66:69], v[180:183], v[158:161], v[66:69]
	v_mfma_f32_16x16x32_bf16 v[28:31], v[180:183], v[164:167], v[28:31]
	v_mfma_f32_16x16x32_bf16 v[32:35], v[180:183], v[168:171], v[32:35]
	v_mfma_f32_16x16x32_bf16 v[48:51], v[180:183], v[172:175], v[48:51]
	v_mfma_f32_16x16x32_bf16 v[70:73], v[192:195], v[158:161], v[70:73]
	v_mfma_f32_16x16x32_bf16 v[56:59], v[192:195], v[164:167], v[56:59]
	v_mfma_f32_16x16x32_bf16 v[74:77], v[192:195], v[168:171], v[74:77]
	v_mfma_f32_16x16x32_bf16 v[52:55], v[192:195], v[172:175], v[52:55]
	v_mfma_f32_16x16x32_bf16 v[2:5], v[210:213], v[158:161], v[2:5]
	v_mfma_f32_16x16x32_bf16 v[10:13], v[210:213], v[164:167], v[10:13]
	v_mfma_f32_16x16x32_bf16 v[36:39], v[210:213], v[168:171], v[36:39]
	v_mfma_f32_16x16x32_bf16 v[14:17], v[210:213], v[172:175], v[14:17]
	s_setprio 0
	v_readlane_b32 s88, v255, 24
	v_readlane_b32 s89, v255, 25
	v_readlane_b32 s90, v255, 26
	v_readlane_b32 s91, v255, 27
	v_readlane_b32 s92, v255, 28
	v_readlane_b32 s93, v255, 29
	v_readlane_b32 s94, v255, 30
	v_readlane_b32 s95, v255, 31
	s_nop 7
	s_nop 1
	s_mul_hi_u32 s43, s43, 0x38e38e39
	s_lshr_b32 s94, s43, 2
	s_mul_i32 s43, s94, 0xfffff700
	s_add_i32 s48, s43, s42
	s_cmpk_lt_i32 s48, 0x800
	s_cselect_b64 s[42:43], -1, 0
	s_mul_i32 s45, s94, 0x6000
	s_and_b64 s[46:47], s[42:43], exec
	v_lshl_or_b32 v7, v8, 6, v7
	s_cselect_b32 s45, s45, 0xc0000
	v_lshl_add_u32 v6, v6, 8, 16
	v_lshlrev_b32_e32 v0, 4, v0
	v_mul_lo_u32 v7, v7, s58
	s_add_u32 s45, s10, s45
	v_add3_u32 v0, v6, v0, v7
	v_mov_b32_e32 v6, v163
	s_addc_u32 s46, s11, 0
	s_lshl_b32 s47, s44, 2
	s_waitcnt vmcnt(0)
	s_barrier
	ds_write_b128 v0, v[62:65]
	ds_write_b128 v0, v[66:69] offset:64
	ds_write_b128 v0, v[70:73] offset:128
	ds_write_b128 v0, v[2:5] offset:192
	ds_write_b128 v0, v[18:21] offset:8448
	ds_write_b128 v0, v[28:31] offset:8512
	ds_write_b128 v0, v[56:59] offset:8576
	ds_write_b128 v0, v[10:13] offset:8640
	ds_write_b128 v0, v[22:25] offset:16896
	ds_write_b128 v0, v[32:35] offset:16960
	ds_write_b128 v0, v[74:77] offset:17024
	ds_write_b128 v0, v[36:39] offset:17088
	ds_write_b128 v0, v[44:47] offset:25344
	ds_write_b128 v0, v[48:51] offset:25408
	ds_write_b128 v0, v[52:55] offset:25472
	ds_write_b128 v0, v[14:17] offset:25536
	s_waitcnt lgkmcnt(0)
	s_barrier
	s_add_u32 s44, s45, s47
	v_lshlrev_b32_e32 v0, 4, v6
	s_addc_u32 s45, s46, 0
	v_and_b32_e32 v0, 0x1f0, v0
	v_lshl_add_u64 v[2:3], s[44:45], 0, v[0:1]
	s_movk_i32 s44, 0x2000
	s_add_i32 s46, s48, 0xfffff800
	s_ashr_i32 s49, s48, 31
	v_add_co_u32_e32 v2, vcc, s44, v2
	s_and_b64 s[44:45], s[42:43], exec
	v_readlane_b32 s64, v251, 1
	v_readlane_b32 s67, v251, 4
	v_readlane_b32 s44, v251, 36
	s_cselect_b32 s50, 23, 20
	v_readlane_b32 s66, v251, 3
	s_cselect_b32 s51, s67, s44
	v_readlane_b32 s44, v251, 35
	s_cselect_b32 s52, s66, s44
	s_cselect_b32 s45, s49, 0
	s_cselect_b32 s44, s48, s46
	s_lshl_b32 s46, s94, s50
	s_add_u32 s46, s52, s46
	s_addc_u32 s48, s51, 0
	s_lshl_b64 s[44:45], s[44:45], 12
	s_add_u32 s49, s46, s44
	s_addc_u32 s51, s48, s45
	s_and_b64 s[42:43], s[42:43], exec
	s_cselect_b32 s52, s69, s73
	s_cselect_b32 s53, s68, s72
	s_lshl_b64 s[42:43], s[94:95], s50
	s_add_u32 s50, s53, s42
	s_addc_u32 s52, s52, s43
	s_and_b64 s[42:43], s[6:7], exec
	s_cselect_b32 s43, s46, s50
	s_cselect_b32 s42, s48, s52
	s_add_u32 s44, s43, s44
	s_addc_u32 s45, s42, s45
	s_add_u32 s42, s49, s47
	s_addc_u32 s43, s51, 0
	v_lshl_add_u64 v[14:15], s[42:43], 0, v[0:1]
	v_ashrrev_i32_e32 v48, 5, v6
	s_add_u32 s42, s44, s47
	s_addc_u32 s43, s45, 0
	v_ashrrev_i32_e32 v49, 31, v48
	v_lshl_add_u64 v[16:17], s[42:43], 0, v[0:1]
	v_lshlrev_b64 v[18:19], 12, v[48:49]
	v_addc_co_u32_e32 v3, vcc, 0, v3, vcc
	v_lshl_add_u64 v[6:7], v[16:17], 0, v[18:19]
	global_load_dwordx4 v[2:5], v[2:3], off
	s_mov_b64 s[42:43], 0x8000
	global_load_dwordx4 v[24:27], v[6:7], off
	v_lshl_add_u64 v[52:53], v[18:19], 0, s[42:43]
	v_lshl_add_u64 v[6:7], v[16:17], 0, v[52:53]
	global_load_dwordx4 v[28:31], v[6:7], off
	v_lshl_add_u64 v[54:55], v[18:19], 0, s[90:91]
	v_lshl_add_u64 v[6:7], v[16:17], 0, v[54:55]
	global_load_dwordx4 v[32:35], v[6:7], off
	s_mov_b64 s[42:43], 0x18000
	v_lshl_add_u64 v[56:57], v[18:19], 0, s[42:43]
	v_lshl_add_u64 v[6:7], v[16:17], 0, v[56:57]
	global_load_dwordx4 v[36:39], v[6:7], off
	v_lshl_add_u64 v[58:59], v[18:19], 0, s[92:93]
	v_lshl_add_u64 v[6:7], v[16:17], 0, v[58:59]
	global_load_dwordx4 v[40:43], v[6:7], off
	s_mov_b64 s[42:43], 0x28000
	v_lshl_add_u64 v[60:61], v[18:19], 0, s[42:43]
	v_lshl_add_u64 v[6:7], v[16:17], 0, v[60:61]
	global_load_dwordx4 v[44:47], v[6:7], off
	v_lshl_add_u64 v[22:23], v[18:19], 0, s[0:1]
	v_lshl_add_u64 v[6:7], v[16:17], 0, v[22:23]
	global_load_dwordx4 v[10:13], v[6:7], off
	s_mov_b64 s[0:1], 0x38000
	v_lshl_add_u64 v[20:21], v[18:19], 0, s[0:1]
	v_lshl_add_u64 v[6:7], v[16:17], 0, v[20:21]
	global_load_dwordx4 v[6:9], v[6:7], off
	v_mul_lo_u32 v48, v48, s58
	v_add3_u32 v0, 16, v0, v48
	ds_read_b128 v[48:51], v0
	v_lshl_add_u64 v[22:23], v[14:15], 0, v[22:23]
	s_mov_b64 s[0:1], 0x40000
	s_mov_b64 s[42:43], 0x48000
	v_readlane_b32 s65, v251, 2
	s_waitcnt vmcnt(7) lgkmcnt(0)
;     DEV void operator()(int tm, int tn, const float* Ct) const {
;     ...
; #pragma unroll
;         for (int it0 = 0; it0 < 16; it0 += 8) {
;             f32x4 xv[8];
; #pragma unroll
;             for (int u = 0; u < 8; ++u) xv[u] = *(const f32x4*)(xs + (size_t)(rb + 8 * (it0 + u)) * D);
; #pragma unroll
;             for (int u = 0; u < 8; ++u) { const int r = rb + 8 * (it0 + u); *(f32x4*)(x0 + (size_t)r * D) = xv[u] + g * *(const f32x4*)(Ct + r * CP + c); }
;         }
	v_pk_fma_f32 v[26:27], v[4:5], v[50:51], v[26:27]
	v_pk_fma_f32 v[24:25], v[2:3], v[48:49], v[24:25]
	v_lshl_add_u64 v[48:49], v[14:15], 0, v[18:19]
	global_store_dwordx4 v[48:49], v[24:27], off
	ds_read_b128 v[24:27], v0 offset:4224
	v_lshl_add_u64 v[50:51], v[18:19], 0, s[0:1]
	s_mov_b64 s[0:1], 0x50000
	s_waitcnt vmcnt(7) lgkmcnt(0)
	v_pk_fma_f32 v[26:27], v[4:5], v[26:27], v[30:31]
	v_pk_fma_f32 v[24:25], v[2:3], v[24:25], v[28:29]
	v_lshl_add_u64 v[28:29], v[14:15], 0, v[52:53]
	global_store_dwordx4 v[28:29], v[24:27], off
	ds_read_b128 v[24:27], v0 offset:8448
	v_lshl_add_u64 v[28:29], v[14:15], 0, v[54:55]
	v_lshl_add_u64 v[52:53], v[18:19], 0, s[42:43]
	v_lshl_add_u64 v[54:55], v[18:19], 0, s[0:1]
	s_mov_b64 s[0:1], 0x58000
	s_waitcnt vmcnt(7) lgkmcnt(0)
	v_pk_fma_f32 v[26:27], v[4:5], v[26:27], v[34:35]
	v_pk_fma_f32 v[24:25], v[2:3], v[24:25], v[32:33]
	global_store_dwordx4 v[28:29], v[24:27], off
	ds_read_b128 v[24:27], v0 offset:12672
	v_lshl_add_u64 v[28:29], v[14:15], 0, v[56:57]
	v_lshl_add_u64 v[56:57], v[18:19], 0, s[0:1]
	s_mov_b64 s[0:1], 0x60000
	s_waitcnt vmcnt(7) lgkmcnt(0)
	v_pk_fma_f32 v[26:27], v[4:5], v[26:27], v[38:39]
	v_pk_fma_f32 v[24:25], v[2:3], v[24:25], v[36:37]
	global_store_dwordx4 v[28:29], v[24:27], off
	ds_read_b128 v[24:27], v0 offset:16896
	v_lshl_add_u64 v[28:29], v[14:15], 0, v[58:59]
	v_lshl_add_u64 v[58:59], v[18:19], 0, s[0:1]
	s_mov_b64 s[0:1], 0x68000
	s_waitcnt vmcnt(7) lgkmcnt(0)
	v_pk_fma_f32 v[26:27], v[4:5], v[26:27], v[42:43]
	v_pk_fma_f32 v[24:25], v[2:3], v[24:25], v[40:41]
	global_store_dwordx4 v[28:29], v[24:27], off
	ds_read_b128 v[24:27], v0 offset:21120
	v_lshl_add_u64 v[28:29], v[14:15], 0, v[60:61]
	v_lshl_add_u64 v[60:61], v[18:19], 0, s[0:1]
	s_mov_b64 s[0:1], 0x70000
	s_waitcnt vmcnt(7) lgkmcnt(0)
	v_pk_fma_f32 v[26:27], v[4:5], v[26:27], v[46:47]
	v_pk_fma_f32 v[24:25], v[2:3], v[24:25], v[44:45]
	global_store_dwordx4 v[28:29], v[24:27], off
	ds_read_b128 v[24:27], v0 offset:25344
	ds_read_b128 v[46:49], v0 offset:33792
	s_waitcnt vmcnt(7) lgkmcnt(1)
	v_pk_fma_f32 v[12:13], v[4:5], v[26:27], v[12:13]
	v_pk_fma_f32 v[10:11], v[2:3], v[24:25], v[10:11]
	global_store_dwordx4 v[22:23], v[10:13], off
	ds_read_b128 v[10:13], v0 offset:29568
	s_waitcnt vmcnt(7) lgkmcnt(0)
	v_pk_fma_f32 v[8:9], v[4:5], v[12:13], v[8:9]
	v_pk_fma_f32 v[6:7], v[2:3], v[10:11], v[6:7]
	v_lshl_add_u64 v[10:11], v[14:15], 0, v[20:21]
	global_store_dwordx4 v[10:11], v[6:9], off
	v_lshl_add_u64 v[20:21], v[18:19], 0, s[0:1]
	s_mov_b64 s[0:1], 0x78000
	v_lshl_add_u64 v[6:7], v[16:17], 0, v[50:51]
	global_load_dwordx4 v[22:25], v[6:7], off
	v_lshl_add_u64 v[6:7], v[16:17], 0, v[52:53]
	global_load_dwordx4 v[26:29], v[6:7], off
	v_lshl_add_u64 v[6:7], v[16:17], 0, v[54:55]
	global_load_dwordx4 v[30:33], v[6:7], off
	v_lshl_add_u64 v[6:7], v[16:17], 0, v[56:57]
	global_load_dwordx4 v[34:37], v[6:7], off
	v_lshl_add_u64 v[6:7], v[16:17], 0, v[58:59]
	global_load_dwordx4 v[38:41], v[6:7], off
	v_lshl_add_u64 v[6:7], v[16:17], 0, v[60:61]
	global_load_dwordx4 v[42:45], v[6:7], off
	v_lshl_add_u64 v[6:7], v[16:17], 0, v[20:21]
	global_load_dwordx4 v[10:13], v[6:7], off
	v_lshl_add_u64 v[18:19], v[18:19], 0, s[0:1]
	v_lshl_add_u64 v[6:7], v[16:17], 0, v[18:19]
	global_load_dwordx4 v[6:9], v[6:7], off
	v_lshl_add_u64 v[16:17], v[14:15], 0, v[50:51]
	s_waitcnt vmcnt(7)
	v_pk_fma_f32 v[24:25], v[4:5], v[48:49], v[24:25]
	v_pk_fma_f32 v[22:23], v[2:3], v[46:47], v[22:23]
	global_store_dwordx4 v[16:17], v[22:25], off
	ds_read_b128 v[22:25], v0 offset:38016
	v_lshl_add_u64 v[16:17], v[14:15], 0, v[52:53]
	s_waitcnt vmcnt(7) lgkmcnt(0)
	v_pk_fma_f32 v[24:25], v[4:5], v[24:25], v[28:29]
	v_pk_fma_f32 v[22:23], v[2:3], v[22:23], v[26:27]
	global_store_dwordx4 v[16:17], v[22:25], off
	ds_read_b128 v[22:25], v0 offset:42240
	v_lshl_add_u64 v[16:17], v[14:15], 0, v[54:55]
	s_waitcnt vmcnt(7) lgkmcnt(0)
	v_pk_fma_f32 v[24:25], v[4:5], v[24:25], v[32:33]
	v_pk_fma_f32 v[22:23], v[2:3], v[22:23], v[30:31]
	global_store_dwordx4 v[16:17], v[22:25], off
	ds_read_b128 v[22:25], v0 offset:46464
	v_lshl_add_u64 v[16:17], v[14:15], 0, v[56:57]
	s_waitcnt vmcnt(7) lgkmcnt(0)
	v_pk_fma_f32 v[24:25], v[4:5], v[24:25], v[36:37]
	v_pk_fma_f32 v[22:23], v[2:3], v[22:23], v[34:35]
	global_store_dwordx4 v[16:17], v[22:25], off
	ds_read_b128 v[22:25], v0 offset:50688
	v_lshl_add_u64 v[16:17], v[14:15], 0, v[58:59]
	s_waitcnt vmcnt(7) lgkmcnt(0)
	v_pk_fma_f32 v[24:25], v[4:5], v[24:25], v[40:41]
	v_pk_fma_f32 v[22:23], v[2:3], v[22:23], v[38:39]
	global_store_dwordx4 v[16:17], v[22:25], off
	ds_read_b128 v[22:25], v0 offset:54912
	v_lshl_add_u64 v[16:17], v[14:15], 0, v[60:61]
	s_waitcnt vmcnt(7) lgkmcnt(0)
	v_pk_fma_f32 v[24:25], v[4:5], v[24:25], v[44:45]
	v_pk_fma_f32 v[22:23], v[2:3], v[22:23], v[42:43]
	global_store_dwordx4 v[16:17], v[22:25], off
	ds_read_b128 v[22:25], v0 offset:59136
	v_lshl_add_u64 v[16:17], v[14:15], 0, v[20:21]
	s_waitcnt vmcnt(7) lgkmcnt(0)
	v_pk_fma_f32 v[12:13], v[4:5], v[24:25], v[12:13]
	v_pk_fma_f32 v[10:11], v[2:3], v[22:23], v[10:11]
	global_store_dwordx4 v[16:17], v[10:13], off
	ds_read_b128 v[10:13], v0 offset:63360
	s_waitcnt vmcnt(7) lgkmcnt(0)
	v_pk_fma_f32 v[4:5], v[4:5], v[12:13], v[8:9]
	v_pk_fma_f32 v[2:3], v[2:3], v[10:11], v[6:7]
	v_lshl_add_u64 v[6:7], v[14:15], 0, v[18:19]
	global_store_dwordx4 v[6:7], v[2:5], off
	s_barrier
	s_branch .LBB0_161

; #define G_MMA(ks_) __builtin_amdgcn_s_setprio(1); _Pragma("unroll") for (int m = 0; m < 4; ++m) \
;         _Pragma("unroll") for (int n = 0; n < 4; ++n) acc[m][n] = __builtin_amdgcn_mfma_f32_16x16x32_bf16(bfv##ks_[n], af##ks_[m], acc[m][n], 0, 0, 0); __builtin_amdgcn_s_setprio(0);
; template <class Epi>
; DEV void gemm_tile(const bf16_t* __restrict__ A, int lda, const bf16_t* __restrict__ Bt, int ldb, int K, int tm, int tn, char* smem, const Epi& epi) {
;     ...
;     for (int kt = 0; kt < nk; ++kt) {
;         const int cur = kt & 1;
;         if (kt + 1 < nk) G_DMA(cur ^ 1, kt + 1);
;         {
;             G_FRAGS(cur, 0)
;             G_MMA(0)
;             G_FRAGS(cur, 1)
;             G_MMA(1)
;         }
;         asm volatile("s_waitcnt vmcnt(0)" ::: "memory");
;         __syncthreads();
.Lgemm_down_loop:
	s_waitcnt lgkmcnt(0)
	v_mfma_f32_16x16x32_bf16 v[62:65], v[142:145], v[126:129], v[62:65]
	ds_read_b128 v[158:161], v214
	v_mfma_f32_16x16x32_bf16 v[14:17], v[142:145], v[130:133], v[14:17]
	v_mfma_f32_16x16x32_bf16 v[26:29], v[142:145], v[134:137], v[26:29]
	ds_read_b128 v[164:167], v214 offset:2048
	v_mfma_f32_16x16x32_bf16 v[46:49], v[142:145], v[138:141], v[46:49]
	v_mfma_f32_16x16x32_bf16 v[66:69], v[146:149], v[126:129], v[66:69]
	ds_read_b128 v[168:171], v214 offset:4096
	v_mfma_f32_16x16x32_bf16 v[22:25], v[146:149], v[130:133], v[22:25]
	v_mfma_f32_16x16x32_bf16 v[34:37], v[146:149], v[134:137], v[34:37]
	ds_read_b128 v[172:175], v214 offset:6144
	v_mfma_f32_16x16x32_bf16 v[50:53], v[146:149], v[138:141], v[50:53]
	v_mfma_f32_16x16x32_bf16 v[70:73], v[150:153], v[126:129], v[70:73]
	ds_read_b128 v[176:179], v216 offset:32768
	v_mfma_f32_16x16x32_bf16 v[30:33], v[150:153], v[130:133], v[30:33]
	v_mfma_f32_16x16x32_bf16 v[58:61], v[150:153], v[134:137], v[58:61]
	ds_read_b128 v[180:183], v216 offset:34816
	v_mfma_f32_16x16x32_bf16 v[54:57], v[150:153], v[138:141], v[54:57]
	v_mfma_f32_16x16x32_bf16 v[2:5], v[154:157], v[126:129], v[2:5]
	ds_read_b128 v[192:195], v216 offset:36864
	v_mfma_f32_16x16x32_bf16 v[18:21], v[154:157], v[130:133], v[18:21]
	v_mfma_f32_16x16x32_bf16 v[38:41], v[154:157], v[134:137], v[38:41]
	ds_read_b128 v[210:213], v216 offset:38912
	v_mfma_f32_16x16x32_bf16 v[10:13], v[154:157], v[138:141], v[10:13]
	s_waitcnt vmcnt(0) lgkmcnt(0)
	s_barrier
	s_mov_b32 m0, s93
	v_mfma_f32_16x16x32_bf16 v[62:65], v[176:179], v[158:161], v[62:65]
	global_load_lds_dwordx4 v250, s[88:89]
	s_add_u32 m0, m0, 0x1000
	ds_read_b128 v[126:129], v184 offset:16384
	v_mfma_f32_16x16x32_bf16 v[14:17], v[176:179], v[164:167], v[14:17]
	global_load_lds_dwordx4 v249, s[88:89]
	s_add_u32 m0, m0, 0x1000
	ds_read_b128 v[130:133], v184 offset:18432
	v_mfma_f32_16x16x32_bf16 v[26:29], v[176:179], v[168:171], v[26:29]
	global_load_lds_dwordx4 v248, s[88:89]
	s_add_u32 m0, m0, 0x1000
	ds_read_b128 v[134:137], v184 offset:20480
	v_mfma_f32_16x16x32_bf16 v[46:49], v[176:179], v[172:175], v[46:49]
	global_load_lds_dwordx4 v247, s[88:89]
	s_add_u32 m0, m0, 0x5000
	ds_read_b128 v[138:141], v184 offset:22528
	v_mfma_f32_16x16x32_bf16 v[66:69], v[180:183], v[158:161], v[66:69]
	global_load_lds_dwordx4 v246, s[90:91]
	s_add_u32 m0, m0, 0x1000
	ds_read_b128 v[142:145], v215 offset:49152
	v_mfma_f32_16x16x32_bf16 v[22:25], v[180:183], v[164:167], v[22:25]
	global_load_lds_dwordx4 v245, s[90:91]
	s_add_u32 m0, m0, 0x1000
	ds_read_b128 v[146:149], v215 offset:51200
	v_mfma_f32_16x16x32_bf16 v[34:37], v[180:183], v[168:171], v[34:37]
	global_load_lds_dwordx4 v244, s[90:91]
	s_add_u32 m0, m0, 0x1000
	ds_read_b128 v[150:153], v215 offset:53248
	v_mfma_f32_16x16x32_bf16 v[50:53], v[180:183], v[172:175], v[50:53]
	global_load_lds_dwordx4 v243, s[90:91]
	ds_read_b128 v[154:157], v215 offset:55296
	v_mfma_f32_16x16x32_bf16 v[70:73], v[192:195], v[158:161], v[70:73]
	s_add_u32 s88, s88, 0x80
	v_mfma_f32_16x16x32_bf16 v[30:33], v[192:195], v[164:167], v[30:33]
	s_addc_u32 s89, s89, 0
	v_mfma_f32_16x16x32_bf16 v[58:61], v[192:195], v[168:171], v[58:61]
	s_add_u32 s90, s90, 0x80
	v_mfma_f32_16x16x32_bf16 v[54:57], v[192:195], v[172:175], v[54:57]
	s_addc_u32 s91, s91, 0
	v_mfma_f32_16x16x32_bf16 v[2:5], v[210:213], v[158:161], v[2:5]
	v_mfma_f32_16x16x32_bf16 v[18:21], v[210:213], v[164:167], v[18:21]
	v_mfma_f32_16x16x32_bf16 v[38:41], v[210:213], v[168:171], v[38:41]
	v_mfma_f32_16x16x32_bf16 v[10:13], v[210:213], v[172:175], v[10:13]
	s_waitcnt lgkmcnt(0)
	v_mfma_f32_16x16x32_bf16 v[62:65], v[142:145], v[126:129], v[62:65]
	ds_read_b128 v[158:161], v214 offset:16384
	v_mfma_f32_16x16x32_bf16 v[14:17], v[142:145], v[130:133], v[14:17]
	v_mfma_f32_16x16x32_bf16 v[26:29], v[142:145], v[134:137], v[26:29]
	ds_read_b128 v[164:167], v214 offset:18432
	v_mfma_f32_16x16x32_bf16 v[46:49], v[142:145], v[138:141], v[46:49]
	v_mfma_f32_16x16x32_bf16 v[66:69], v[146:149], v[126:129], v[66:69]
	ds_read_b128 v[168:171], v214 offset:20480
	v_mfma_f32_16x16x32_bf16 v[22:25], v[146:149], v[130:133], v[22:25]
	v_mfma_f32_16x16x32_bf16 v[34:37], v[146:149], v[134:137], v[34:37]
	ds_read_b128 v[172:175], v214 offset:22528
	v_mfma_f32_16x16x32_bf16 v[50:53], v[146:149], v[138:141], v[50:53]
	v_mfma_f32_16x16x32_bf16 v[70:73], v[150:153], v[126:129], v[70:73]
	ds_read_b128 v[176:179], v216 offset:49152
	v_mfma_f32_16x16x32_bf16 v[30:33], v[150:153], v[130:133], v[30:33]
	v_mfma_f32_16x16x32_bf16 v[58:61], v[150:153], v[134:137], v[58:61]
	ds_read_b128 v[180:183], v216 offset:51200
	v_mfma_f32_16x16x32_bf16 v[54:57], v[150:153], v[138:141], v[54:57]
	v_mfma_f32_16x16x32_bf16 v[2:5], v[154:157], v[126:129], v[2:5]
	ds_read_b128 v[192:195], v216 offset:53248
	v_mfma_f32_16x16x32_bf16 v[18:21], v[154:157], v[130:133], v[18:21]
	v_mfma_f32_16x16x32_bf16 v[38:41], v[154:157], v[134:137], v[38:41]
	ds_read_b128 v[210:213], v216 offset:55296
	v_mfma_f32_16x16x32_bf16 v[10:13], v[154:157], v[138:141], v[10:13]
	s_waitcnt vmcnt(0) lgkmcnt(0)
	s_barrier
; #define G_MMA(ks_) __builtin_amdgcn_s_setprio(1); _Pragma("unroll") for (int m = 0; m < 4; ++m) \
;         _Pragma("unroll") for (int n = 0; n < 4; ++n) acc[m][n] = __builtin_amdgcn_mfma_f32_16x16x32_bf16(bfv##ks_[n], af##ks_[m], acc[m][n], 0, 0, 0); __builtin_amdgcn_s_setprio(0);
; template <class Epi>
; DEV void gemm_tile(const bf16_t* __restrict__ A, int lda, const bf16_t* __restrict__ Bt, int ldb, int K, int tm, int tn, char* smem, const Epi& epi) {
;     ...
;     for (int kt = 0; kt < nk; ++kt) {
;         const int cur = kt & 1;
;         if (kt + 1 < nk) G_DMA(cur ^ 1, kt + 1);
;         {
;             G_FRAGS(cur, 0)
;             G_MMA(0)
;             G_FRAGS(cur, 1)
;             G_MMA(1)
;         }
;         asm volatile("s_waitcnt vmcnt(0)" ::: "memory");
;         __syncthreads();
;     }
	s_mov_b32 m0, s94
	v_mfma_f32_16x16x32_bf16 v[62:65], v[176:179], v[158:161], v[62:65]
	global_load_lds_dwordx4 v250, s[88:89]
	s_add_u32 m0, m0, 0x1000
	ds_read_b128 v[126:129], v184
	v_mfma_f32_16x16x32_bf16 v[14:17], v[176:179], v[164:167], v[14:17]
	global_load_lds_dwordx4 v249, s[88:89]
	s_add_u32 m0, m0, 0x1000
	ds_read_b128 v[130:133], v184 offset:2048
	v_mfma_f32_16x16x32_bf16 v[26:29], v[176:179], v[168:171], v[26:29]
	global_load_lds_dwordx4 v248, s[88:89]
	s_add_u32 m0, m0, 0x1000
	ds_read_b128 v[134:137], v184 offset:4096
	v_mfma_f32_16x16x32_bf16 v[46:49], v[176:179], v[172:175], v[46:49]
	global_load_lds_dwordx4 v247, s[88:89]
	s_add_u32 m0, m0, 0x5000
	ds_read_b128 v[138:141], v184 offset:6144
	v_mfma_f32_16x16x32_bf16 v[66:69], v[180:183], v[158:161], v[66:69]
	global_load_lds_dwordx4 v246, s[90:91]
	s_add_u32 m0, m0, 0x1000
	ds_read_b128 v[142:145], v215 offset:32768
	v_mfma_f32_16x16x32_bf16 v[22:25], v[180:183], v[164:167], v[22:25]
	global_load_lds_dwordx4 v245, s[90:91]
	s_add_u32 m0, m0, 0x1000
	ds_read_b128 v[146:149], v215 offset:34816
	v_mfma_f32_16x16x32_bf16 v[34:37], v[180:183], v[168:171], v[34:37]
	global_load_lds_dwordx4 v244, s[90:91]
	s_add_u32 m0, m0, 0x1000
	ds_read_b128 v[150:153], v215 offset:36864
	v_mfma_f32_16x16x32_bf16 v[50:53], v[180:183], v[172:175], v[50:53]
	global_load_lds_dwordx4 v243, s[90:91]
	ds_read_b128 v[154:157], v215 offset:38912
	v_mfma_f32_16x16x32_bf16 v[70:73], v[192:195], v[158:161], v[70:73]
	s_add_u32 s88, s88, 0x80
	v_mfma_f32_16x16x32_bf16 v[30:33], v[192:195], v[164:167], v[30:33]
	s_addc_u32 s89, s89, 0
	v_mfma_f32_16x16x32_bf16 v[58:61], v[192:195], v[168:171], v[58:61]
	s_add_u32 s90, s90, 0x80
	v_mfma_f32_16x16x32_bf16 v[54:57], v[192:195], v[172:175], v[54:57]
	s_addc_u32 s91, s91, 0
	v_mfma_f32_16x16x32_bf16 v[2:5], v[210:213], v[158:161], v[2:5]
	v_mfma_f32_16x16x32_bf16 v[18:21], v[210:213], v[164:167], v[18:21]
	v_mfma_f32_16x16x32_bf16 v[38:41], v[210:213], v[168:171], v[38:41]
	v_mfma_f32_16x16x32_bf16 v[10:13], v[210:213], v[172:175], v[10:13]
	s_sub_u32 s92, s92, 1
	s_cmp_lg_u32 s92, 0
	s_cbranch_scc1 .Lgemm_down_loop
	s_waitcnt lgkmcnt(0)
	v_mfma_f32_16x16x32_bf16 v[62:65], v[142:145], v[126:129], v[62:65]
	ds_read_b128 v[158:161], v214
	v_mfma_f32_16x16x32_bf16 v[14:17], v[142:145], v[130:133], v[14:17]
	v_mfma_f32_16x16x32_bf16 v[26:29], v[142:145], v[134:137], v[26:29]
	ds_read_b128 v[164:167], v214 offset:2048
	v_mfma_f32_16x16x32_bf16 v[46:49], v[142:145], v[138:141], v[46:49]
	v_mfma_f32_16x16x32_bf16 v[66:69], v[146:149], v[126:129], v[66:69]
	ds_read_b128 v[168:171], v214 offset:4096
	v_mfma_f32_16x16x32_bf16 v[22:25], v[146:149], v[130:133], v[22:25]
	v_mfma_f32_16x16x32_bf16 v[34:37], v[146:149], v[134:137], v[34:37]
	ds_read_b128 v[172:175], v214 offset:6144
	v_mfma_f32_16x16x32_bf16 v[50:53], v[146:149], v[138:141], v[50:53]
	v_mfma_f32_16x16x32_bf16 v[70:73], v[150:153], v[126:129], v[70:73]
	ds_read_b128 v[176:179], v216 offset:32768
	v_mfma_f32_16x16x32_bf16 v[30:33], v[150:153], v[130:133], v[30:33]
	v_mfma_f32_16x16x32_bf16 v[58:61], v[150:153], v[134:137], v[58:61]
	ds_read_b128 v[180:183], v216 offset:34816
	v_mfma_f32_16x16x32_bf16 v[54:57], v[150:153], v[138:141], v[54:57]
	v_mfma_f32_16x16x32_bf16 v[2:5], v[154:157], v[126:129], v[2:5]
	ds_read_b128 v[192:195], v216 offset:36864
	v_mfma_f32_16x16x32_bf16 v[18:21], v[154:157], v[130:133], v[18:21]
	v_mfma_f32_16x16x32_bf16 v[38:41], v[154:157], v[134:137], v[38:41]
	ds_read_b128 v[210:213], v216 offset:38912
	v_mfma_f32_16x16x32_bf16 v[10:13], v[154:157], v[138:141], v[10:13]
	s_waitcnt vmcnt(0) lgkmcnt(0)
	s_barrier
	v_mfma_f32_16x16x32_bf16 v[62:65], v[176:179], v[158:161], v[62:65]
	ds_read_b128 v[126:129], v184 offset:16384
	v_mfma_f32_16x16x32_bf16 v[14:17], v[176:179], v[164:167], v[14:17]
	ds_read_b128 v[130:133], v184 offset:18432
	v_mfma_f32_16x16x32_bf16 v[26:29], v[176:179], v[168:171], v[26:29]
	ds_read_b128 v[134:137], v184 offset:20480
	v_mfma_f32_16x16x32_bf16 v[46:49], v[176:179], v[172:175], v[46:49]
	ds_read_b128 v[138:141], v184 offset:22528
	v_mfma_f32_16x16x32_bf16 v[66:69], v[180:183], v[158:161], v[66:69]
	ds_read_b128 v[142:145], v215 offset:49152
	v_mfma_f32_16x16x32_bf16 v[22:25], v[180:183], v[164:167], v[22:25]
	ds_read_b128 v[146:149], v215 offset:51200
	v_mfma_f32_16x16x32_bf16 v[34:37], v[180:183], v[168:171], v[34:37]
	ds_read_b128 v[150:153], v215 offset:53248
	v_mfma_f32_16x16x32_bf16 v[50:53], v[180:183], v[172:175], v[50:53]
	ds_read_b128 v[154:157], v215 offset:55296
	v_mfma_f32_16x16x32_bf16 v[70:73], v[192:195], v[158:161], v[70:73]
	v_mfma_f32_16x16x32_bf16 v[30:33], v[192:195], v[164:167], v[30:33]
	v_mfma_f32_16x16x32_bf16 v[58:61], v[192:195], v[168:171], v[58:61]
	v_mfma_f32_16x16x32_bf16 v[54:57], v[192:195], v[172:175], v[54:57]
	v_mfma_f32_16x16x32_bf16 v[2:5], v[210:213], v[158:161], v[2:5]
	v_mfma_f32_16x16x32_bf16 v[18:21], v[210:213], v[164:167], v[18:21]
	v_mfma_f32_16x16x32_bf16 v[38:41], v[210:213], v[168:171], v[38:41]
	v_mfma_f32_16x16x32_bf16 v[10:13], v[210:213], v[172:175], v[10:13]
	s_waitcnt lgkmcnt(0)
	v_mfma_f32_16x16x32_bf16 v[62:65], v[142:145], v[126:129], v[62:65]
	ds_read_b128 v[158:161], v214 offset:16384
	v_mfma_f32_16x16x32_bf16 v[14:17], v[142:145], v[130:133], v[14:17]
	v_mfma_f32_16x16x32_bf16 v[26:29], v[142:145], v[134:137], v[26:29]
	ds_read_b128 v[164:167], v214 offset:18432
	v_mfma_f32_16x16x32_bf16 v[46:49], v[142:145], v[138:141], v[46:49]
	v_mfma_f32_16x16x32_bf16 v[66:69], v[146:149], v[126:129], v[66:69]
	ds_read_b128 v[168:171], v214 offset:20480
	v_mfma_f32_16x16x32_bf16 v[22:25], v[146:149], v[130:133], v[22:25]
	v_mfma_f32_16x16x32_bf16 v[34:37], v[146:149], v[134:137], v[34:37]
	ds_read_b128 v[172:175], v214 offset:22528
	v_mfma_f32_16x16x32_bf16 v[50:53], v[146:149], v[138:141], v[50:53]
	v_mfma_f32_16x16x32_bf16 v[70:73], v[150:153], v[126:129], v[70:73]
	ds_read_b128 v[176:179], v216 offset:49152
	v_mfma_f32_16x16x32_bf16 v[30:33], v[150:153], v[130:133], v[30:33]
	v_mfma_f32_16x16x32_bf16 v[58:61], v[150:153], v[134:137], v[58:61]
	ds_read_b128 v[180:183], v216 offset:51200
	v_mfma_f32_16x16x32_bf16 v[54:57], v[150:153], v[138:141], v[54:57]
	v_mfma_f32_16x16x32_bf16 v[2:5], v[154:157], v[126:129], v[2:5]
	ds_read_b128 v[192:195], v216 offset:53248
	v_mfma_f32_16x16x32_bf16 v[18:21], v[154:157], v[130:133], v[18:21]
	v_mfma_f32_16x16x32_bf16 v[38:41], v[154:157], v[134:137], v[38:41]
	ds_read_b128 v[210:213], v216 offset:55296
	v_mfma_f32_16x16x32_bf16 v[10:13], v[154:157], v[138:141], v[10:13]
	s_waitcnt lgkmcnt(0)
	s_barrier
; DEV int tid_() { int t = __builtin_amdgcn_workitem_id_x(); asm volatile("" : "+v"(t)); return t; }
; #define G_MMA(ks_) __builtin_amdgcn_s_setprio(1); _Pragma("unroll") for (int m = 0; m < 4; ++m) \
;         _Pragma("unroll") for (int n = 0; n < 4; ++n) acc[m][n] = __builtin_amdgcn_mfma_f32_16x16x32_bf16(bfv##ks_[n], af##ks_[m], acc[m][n], 0, 0, 0); __builtin_amdgcn_s_setprio(0);
; template <class Epi>
; DEV void gemm_tile(const bf16_t* __restrict__ A, int lda, const bf16_t* __restrict__ Bt, int ldb, int K, int tm, int tn, char* smem, const Epi& epi) {
;     ...
;     for (int kt = 0; kt < nk; ++kt) {
;         const int cur = kt & 1;
;         if (kt + 1 < nk) G_DMA(cur ^ 1, kt + 1);
;         {
;             G_FRAGS(cur, 0)
;             G_MMA(0)
;             G_FRAGS(cur, 1)
;             G_MMA(1)
;         }
;         asm volatile("s_waitcnt vmcnt(0)" ::: "memory");
;         __syncthreads();
;     }
;     ...
;     float* Ct = (float*)smem;
; #pragma unroll
;     for (int m = 0; m < 4; ++m)
; #pragma unroll
;         for (int n = 0; n < 4; ++n) *(f32x4*)(Ct + (wr * 64 + m * 16 + fr) * CP + wc * 64 + n * 16 + fq * 4) = acc[m][n];
;     __syncthreads();
;     DEV void operator()(int tm, int tn, const float* Ct) const {
;         const int row0 = tm * 128, b = row0 / TT, tt0 = row0 - b * TT;
;         const int tid = tid_(), c = (tid & 31) << 2, rb = tid >> 5;
;         const f32x4 g = *(const f32x4*)(mod + (size_t)(tt0 < SEQ ? b : 32) * 6144 + goff + tn * 128 + c);
	v_mfma_f32_16x16x32_bf16 v[62:65], v[176:179], v[158:161], v[62:65]
	v_mfma_f32_16x16x32_bf16 v[14:17], v[176:179], v[164:167], v[14:17]
	v_mfma_f32_16x16x32_bf16 v[26:29], v[176:179], v[168:171], v[26:29]
	v_mfma_f32_16x16x32_bf16 v[46:49], v[176:179], v[172:175], v[46:49]
	v_mfma_f32_16x16x32_bf16 v[66:69], v[180:183], v[158:161], v[66:69]
	v_mfma_f32_16x16x32_bf16 v[22:25], v[180:183], v[164:167], v[22:25]
	v_mfma_f32_16x16x32_bf16 v[34:37], v[180:183], v[168:171], v[34:37]
	v_mfma_f32_16x16x32_bf16 v[50:53], v[180:183], v[172:175], v[50:53]
	v_mfma_f32_16x16x32_bf16 v[70:73], v[192:195], v[158:161], v[70:73]
	v_mfma_f32_16x16x32_bf16 v[30:33], v[192:195], v[164:167], v[30:33]
	v_mfma_f32_16x16x32_bf16 v[58:61], v[192:195], v[168:171], v[58:61]
	v_mfma_f32_16x16x32_bf16 v[54:57], v[192:195], v[172:175], v[54:57]
	v_mfma_f32_16x16x32_bf16 v[2:5], v[210:213], v[158:161], v[2:5]
	v_mfma_f32_16x16x32_bf16 v[18:21], v[210:213], v[164:167], v[18:21]
	v_mfma_f32_16x16x32_bf16 v[38:41], v[210:213], v[168:171], v[38:41]
	v_mfma_f32_16x16x32_bf16 v[10:13], v[210:213], v[172:175], v[10:13]
	s_setprio 0
	v_readlane_b32 s88, v255, 24
	v_readlane_b32 s89, v255, 25
	v_readlane_b32 s90, v255, 26
	v_readlane_b32 s91, v255, 27
	v_readlane_b32 s92, v255, 28
	v_readlane_b32 s93, v255, 29
	v_readlane_b32 s94, v255, 30
	v_readlane_b32 s95, v255, 31
	s_nop 7
	s_nop 1
	s_mul_hi_u32 s39, s39, 0x38e38e39
	s_lshr_b32 s46, s39, 2
	s_mul_i32 s39, s46, 0xfffff700
	s_add_i32 s47, s39, s38
	s_cmpk_lt_i32 s47, 0x800
	s_cselect_b64 s[38:39], -1, 0
	s_mul_i32 s43, s46, 0x6000
	s_and_b64 s[44:45], s[38:39], exec
	v_lshl_or_b32 v7, v8, 6, v7
	s_cselect_b32 s43, s43, 0xc0000
	v_lshl_add_u32 v6, v6, 8, 16
	v_lshlrev_b32_e32 v0, 4, v0
	v_mul_lo_u32 v7, v7, s58
	s_add_u32 s43, s10, s43
	v_add3_u32 v0, v6, v0, v7
	v_mov_b32_e32 v8, v163
	s_addc_u32 s44, s11, 0
	s_lshl_b32 s45, s42, 2
	s_waitcnt vmcnt(0)
	s_barrier
	ds_write_b128 v0, v[62:65]
	ds_write_b128 v0, v[66:69] offset:64
	ds_write_b128 v0, v[70:73] offset:128
	ds_write_b128 v0, v[2:5] offset:192
	ds_write_b128 v0, v[14:17] offset:8448
	ds_write_b128 v0, v[22:25] offset:8512
	ds_write_b128 v0, v[30:33] offset:8576
	ds_write_b128 v0, v[18:21] offset:8640
	ds_write_b128 v0, v[26:29] offset:16896
	ds_write_b128 v0, v[34:37] offset:16960
	ds_write_b128 v0, v[58:61] offset:17024
	ds_write_b128 v0, v[38:41] offset:17088
	ds_write_b128 v0, v[46:49] offset:25344
	ds_write_b128 v0, v[50:53] offset:25408
	ds_write_b128 v0, v[54:57] offset:25472
	ds_write_b128 v0, v[10:13] offset:25536
	s_waitcnt lgkmcnt(0)
	s_barrier
; DEV int tid_() { int t = __builtin_amdgcn_workitem_id_x(); asm volatile("" : "+v"(t)); return t; }
; template <class Epi>
; DEV void gemm_tile(const bf16_t* __restrict__ A, int lda, const bf16_t* __restrict__ Bt, int ldb, int K, int tm, int tn, char* smem, const Epi& epi) {
;     ...
;     __syncthreads();
;     DEV void operator()(int tm, int tn, const float* Ct) const {
;         const int row0 = tm * 128, b = row0 / TT, tt0 = row0 - b * TT;
;         const int tid = tid_(), c = (tid & 31) << 2, rb = tid >> 5;
;         const f32x4 g = *(const f32x4*)(mod + (size_t)(tt0 < SEQ ? b : 32) * 6144 + goff + tn * 128 + c);
;         float* x0 = xrow(*p, row0) + tn * 128 + c;
;         const float* xs = from_in ? xrow_in(*p, row0) + tn * 128 + c : x0;
; #pragma unroll
;         for (int it0 = 0; it0 < 16; it0 += 8) {
;             f32x4 xv[8];
; #pragma unroll
;             for (int u = 0; u < 8; ++u) xv[u] = *(const f32x4*)(xs + (size_t)(rb + 8 * (it0 + u)) * D);
; #pragma unroll
;             for (int u = 0; u < 8; ++u) { const int r = rb + 8 * (it0 + u); *(f32x4*)(x0 + (size_t)r * D) = xv[u] + g * *(const f32x4*)(Ct + r * CP + c); }
;         }
;     }
	s_add_u32 s42, s43, s45
	v_lshlrev_b32_e32 v0, 4, v8
	s_addc_u32 s43, s44, 0
	v_and_b32_e32 v0, 0x1f0, v0
	v_lshl_add_u64 v[2:3], s[42:43], 0, v[0:1]
	s_movk_i32 s42, 0x5000
	v_add_co_u32_e32 v2, vcc, s42, v2
	s_add_i32 s42, s47, 0xfffff800
	s_ashr_i32 s43, s47, 31
	s_and_b64 s[38:39], s[38:39], exec
	v_readlane_b32 s48, v251, 1
	v_readlane_b32 s51, v251, 4
	v_readlane_b32 s38, v251, 36
	s_cselect_b32 s44, 23, 20
	v_readlane_b32 s49, v251, 2
	v_readlane_b32 s50, v251, 3
	s_cselect_b32 s48, s51, s38
	v_readlane_b32 s38, v251, 35
	s_cselect_b32 s49, s50, s38
	s_cselect_b32 s39, s43, 0
	s_cselect_b32 s38, s47, s42
	s_lshl_b32 s42, s46, s44
	s_add_u32 s42, s49, s42
	s_addc_u32 s43, s48, 0
	s_lshl_b64 s[38:39], s[38:39], 12
	s_add_u32 s38, s42, s38
	s_addc_u32 s39, s43, s39
	s_add_u32 s38, s38, s45
	v_ashrrev_i32_e32 v40, 5, v8
	s_addc_u32 s39, s39, 0
	v_ashrrev_i32_e32 v41, 31, v40
	v_lshl_add_u64 v[6:7], s[38:39], 0, v[0:1]
	v_lshlrev_b64 v[8:9], 12, v[40:41]
	v_addc_co_u32_e32 v3, vcc, 0, v3, vcc
	v_lshl_add_u64 v[6:7], v[6:7], 0, v[8:9]
	global_load_dwordx4 v[2:5], v[2:3], off
	s_mov_b32 s38, 0x8000
	global_load_dwordx4 v[8:11], v[6:7], off
	v_add_co_u32_e32 v44, vcc, s38, v6
	s_mov_b32 s38, 0x10000
	s_nop 0
	v_addc_co_u32_e32 v45, vcc, 0, v7, vcc
	global_load_dwordx4 v[12:15], v[44:45], off
	v_add_co_u32_e32 v46, vcc, s38, v6
	s_mov_b32 s38, 0x18000
	s_nop 0
	v_addc_co_u32_e32 v47, vcc, 0, v7, vcc
	global_load_dwordx4 v[16:19], v[46:47], off
	v_add_co_u32_e32 v48, vcc, s38, v6
	s_mov_b32 s38, 0x20000
	s_nop 0
	v_addc_co_u32_e32 v49, vcc, 0, v7, vcc
	global_load_dwordx4 v[20:23], v[48:49], off
	v_add_co_u32_e32 v50, vcc, s38, v6
	s_mov_b32 s38, 0x28000
	s_nop 0
	v_addc_co_u32_e32 v51, vcc, 0, v7, vcc
	global_load_dwordx4 v[24:27], v[50:51], off
	v_add_co_u32_e32 v52, vcc, s38, v6
	s_mov_b32 s38, 0x30000
	s_nop 0
	v_addc_co_u32_e32 v53, vcc, 0, v7, vcc
	global_load_dwordx4 v[28:31], v[52:53], off
	v_add_co_u32_e32 v54, vcc, s38, v6
	s_mov_b32 s38, 0x38000
	s_nop 0
	v_addc_co_u32_e32 v55, vcc, 0, v7, vcc
	global_load_dwordx4 v[32:35], v[54:55], off
	v_add_co_u32_e32 v56, vcc, s38, v6
	v_mul_lo_u32 v40, v40, s58
	s_nop 0
	v_addc_co_u32_e32 v57, vcc, 0, v7, vcc
	global_load_dwordx4 v[36:39], v[56:57], off
	v_add3_u32 v0, 16, v0, v40
	ds_read_b128 v[40:43], v0
	s_mov_b32 s38, 0x40000
	s_waitcnt vmcnt(7) lgkmcnt(0)
	v_pk_fma_f32 v[10:11], v[4:5], v[42:43], v[10:11]
	v_pk_fma_f32 v[8:9], v[2:3], v[40:41], v[8:9]
	global_store_dwordx4 v[6:7], v[8:11], off
	ds_read_b128 v[8:11], v0 offset:4224
	s_waitcnt vmcnt(7) lgkmcnt(0)
	v_pk_fma_f32 v[10:11], v[4:5], v[10:11], v[14:15]
	v_pk_fma_f32 v[8:9], v[2:3], v[8:9], v[12:13]
	global_store_dwordx4 v[44:45], v[8:11], off
	ds_read_b128 v[8:11], v0 offset:8448
	s_waitcnt vmcnt(7) lgkmcnt(0)
	v_pk_fma_f32 v[10:11], v[4:5], v[10:11], v[18:19]
	v_pk_fma_f32 v[8:9], v[2:3], v[8:9], v[16:17]
	global_store_dwordx4 v[46:47], v[8:11], off
	ds_read_b128 v[8:11], v0 offset:12672
	s_waitcnt vmcnt(7) lgkmcnt(0)
	v_pk_fma_f32 v[10:11], v[4:5], v[10:11], v[22:23]
	v_pk_fma_f32 v[8:9], v[2:3], v[8:9], v[20:21]
	global_store_dwordx4 v[48:49], v[8:11], off
	ds_read_b128 v[8:11], v0 offset:16896
	s_waitcnt vmcnt(7) lgkmcnt(0)
	v_pk_fma_f32 v[10:11], v[4:5], v[10:11], v[26:27]
	v_pk_fma_f32 v[8:9], v[2:3], v[8:9], v[24:25]
	global_store_dwordx4 v[50:51], v[8:11], off
	ds_read_b128 v[8:11], v0 offset:21120
	ds_read_b128 v[48:51], v0 offset:33792
	s_waitcnt vmcnt(7) lgkmcnt(1)
	v_pk_fma_f32 v[10:11], v[4:5], v[10:11], v[30:31]
	v_pk_fma_f32 v[8:9], v[2:3], v[8:9], v[28:29]
	global_store_dwordx4 v[52:53], v[8:11], off
	ds_read_b128 v[8:11], v0 offset:25344
	v_add_co_u32_e32 v52, vcc, s38, v6
	s_mov_b32 s38, 0x48000
	s_nop 0
	v_addc_co_u32_e32 v53, vcc, 0, v7, vcc
	s_waitcnt vmcnt(7) lgkmcnt(0)
	v_pk_fma_f32 v[10:11], v[4:5], v[10:11], v[34:35]
	v_pk_fma_f32 v[8:9], v[2:3], v[8:9], v[32:33]
	global_store_dwordx4 v[54:55], v[8:11], off
	ds_read_b128 v[8:11], v0 offset:29568
	v_add_co_u32_e32 v54, vcc, s38, v6
	s_mov_b32 s38, 0x50000
	s_nop 0
	v_addc_co_u32_e32 v55, vcc, 0, v7, vcc
	s_waitcnt vmcnt(7) lgkmcnt(0)
	v_pk_fma_f32 v[10:11], v[4:5], v[10:11], v[38:39]
	v_pk_fma_f32 v[8:9], v[2:3], v[8:9], v[36:37]
	global_load_dwordx4 v[36:39], v[52:53], off
	global_load_dwordx4 v[40:43], v[54:55], off
	s_nop 0
	global_store_dwordx4 v[56:57], v[8:11], off
	v_add_co_u32_e32 v56, vcc, s38, v6
	s_mov_b32 s38, 0x58000
	s_nop 0
	v_addc_co_u32_e32 v57, vcc, 0, v7, vcc
	global_load_dwordx4 v[44:47], v[56:57], off
	v_add_co_u32_e32 v34, vcc, s38, v6
	s_mov_b32 s38, 0x60000
	s_nop 0
	v_addc_co_u32_e32 v35, vcc, 0, v7, vcc
	global_load_dwordx4 v[22:25], v[34:35], off
	v_add_co_u32_e32 v32, vcc, s38, v6
	s_mov_b32 s38, 0x68000
	s_nop 0
	v_addc_co_u32_e32 v33, vcc, 0, v7, vcc
	global_load_dwordx4 v[18:21], v[32:33], off
	v_add_co_u32_e32 v30, vcc, s38, v6
	s_mov_b32 s38, 0x70000
	s_nop 0
	v_addc_co_u32_e32 v31, vcc, 0, v7, vcc
	global_load_dwordx4 v[14:17], v[30:31], off
	v_add_co_u32_e32 v28, vcc, s38, v6
	s_mov_b32 s38, 0x78000
	s_nop 0
	v_addc_co_u32_e32 v29, vcc, 0, v7, vcc
	global_load_dwordx4 v[10:13], v[28:29], off
	v_add_co_u32_e32 v26, vcc, s38, v6
	s_waitcnt vmcnt(7)
	v_pk_fma_f32 v[38:39], v[4:5], v[50:51], v[38:39]
	v_addc_co_u32_e32 v27, vcc, 0, v7, vcc
	global_load_dwordx4 v[6:9], v[26:27], off
	v_pk_fma_f32 v[36:37], v[2:3], v[48:49], v[36:37]
	global_store_dwordx4 v[52:53], v[36:39], off
	ds_read_b128 v[36:39], v0 offset:38016
	s_waitcnt vmcnt(8) lgkmcnt(0)
	v_pk_fma_f32 v[38:39], v[4:5], v[38:39], v[42:43]
	v_pk_fma_f32 v[36:37], v[2:3], v[36:37], v[40:41]
	global_store_dwordx4 v[54:55], v[36:39], off
	ds_read_b128 v[36:39], v0 offset:42240
	s_waitcnt vmcnt(7) lgkmcnt(0)
	v_pk_fma_f32 v[38:39], v[4:5], v[38:39], v[46:47]
	v_pk_fma_f32 v[36:37], v[2:3], v[36:37], v[44:45]
	global_store_dwordx4 v[56:57], v[36:39], off
	ds_read_b128 v[36:39], v0 offset:46464
	s_waitcnt vmcnt(7) lgkmcnt(0)
	v_pk_fma_f32 v[24:25], v[4:5], v[38:39], v[24:25]
	v_pk_fma_f32 v[22:23], v[2:3], v[36:37], v[22:23]
	global_store_dwordx4 v[34:35], v[22:25], off
	ds_read_b128 v[22:25], v0 offset:50688
	s_waitcnt vmcnt(7) lgkmcnt(0)
	v_pk_fma_f32 v[20:21], v[4:5], v[24:25], v[20:21]
	v_pk_fma_f32 v[18:19], v[2:3], v[22:23], v[18:19]
	global_store_dwordx4 v[32:33], v[18:21], off
	ds_read_b128 v[18:21], v0 offset:54912
	s_waitcnt vmcnt(7) lgkmcnt(0)
	v_pk_fma_f32 v[16:17], v[4:5], v[20:21], v[16:17]
	v_pk_fma_f32 v[14:15], v[2:3], v[18:19], v[14:15]
	global_store_dwordx4 v[30:31], v[14:17], off
	ds_read_b128 v[14:17], v0 offset:59136
	s_waitcnt vmcnt(7) lgkmcnt(0)
	v_pk_fma_f32 v[12:13], v[4:5], v[16:17], v[12:13]
	v_pk_fma_f32 v[10:11], v[2:3], v[14:15], v[10:11]
	global_store_dwordx4 v[28:29], v[10:13], off
	ds_read_b128 v[10:13], v0 offset:63360
	s_waitcnt vmcnt(7) lgkmcnt(0)
	v_pk_fma_f32 v[4:5], v[4:5], v[12:13], v[8:9]
	v_pk_fma_f32 v[2:3], v[2:3], v[10:11], v[6:7]
	global_store_dwordx4 v[26:27], v[2:5], off
	s_barrier
	s_branch .LBB0_178
